# low-rank expansion GEMM epilogue rewritten by hand: one kind dispatch per tile instead of two scalar branches per element, straight-line activation code
# speedup vs baseline: 1.0964x; 1.0300x over previous
.LBB0_573:
	s_ashr_i32 s55, s8, 1
	s_lshl_b32 s20, s85, 8
	s_add_i32 s20, s20, s93
	v_add_u32_e32 v156, s20, v159
	s_lshl_b32 s9, s8, 8
	s_or_b32 s9, s9, s94
	v_lshl_add_u32 v152, v158, 3, s9
	v_lshlrev_b32_e32 v156, 12, v156
	v_and_b32_e32 v153, 0x1f8, v152
	v_lshl_add_u32 v156, v152, 1, v156
	v_lshlrev_b32_e32 v153, 2, v153
	s_cmp_eq_u32 s55, 2
	s_cbranch_scc1 .Llr_plain
	s_cmp_eq_u32 s55, 0
	s_cselect_b64 s[62:63], s[46:47], s[48:49]
	s_cmp_eq_u32 s55, 3
	s_cselect_b64 s[62:63], s[12:13], s[62:63]
	global_load_dwordx4 v[10:13], v153, s[62:63]
	global_load_dwordx4 v[14:17], v153, s[62:63] offset:16
	s_cmp_eq_u32 s55, 0
	s_cbranch_scc1 .Llr_decay
	s_waitcnt vmcnt(0)
	v_pk_add_f32 v[6:7], v[6:7], v[10:11]
	v_pk_add_f32 v[8:9], v[8:9], v[12:13]
	v_pk_add_f32 v[2:3], v[2:3], v[14:15]
	v_pk_add_f32 v[4:5], v[4:5], v[16:17]
	v_mul_f32_e32 v6, 0xbfb8aa3b, v6
	v_mul_f32_e32 v7, 0xbfb8aa3b, v7
	v_mul_f32_e32 v8, 0xbfb8aa3b, v8
	v_mul_f32_e32 v9, 0xbfb8aa3b, v9
	v_mul_f32_e32 v2, 0xbfb8aa3b, v2
	v_mul_f32_e32 v3, 0xbfb8aa3b, v3
	v_mul_f32_e32 v4, 0xbfb8aa3b, v4
	v_mul_f32_e32 v5, 0xbfb8aa3b, v5
	v_exp_f32_e32 v6, v6
	v_exp_f32_e32 v7, v7
	v_exp_f32_e32 v8, v8
	v_exp_f32_e32 v9, v9
	v_exp_f32_e32 v2, v2
	v_exp_f32_e32 v3, v3
	v_exp_f32_e32 v4, v4
	v_exp_f32_e32 v5, v5
	v_add_f32_e32 v6, 1.0, v6
	v_add_f32_e32 v7, 1.0, v7
	v_add_f32_e32 v8, 1.0, v8
	v_add_f32_e32 v9, 1.0, v9
	v_add_f32_e32 v2, 1.0, v2
	v_add_f32_e32 v3, 1.0, v3
	v_add_f32_e32 v4, 1.0, v4
	v_add_f32_e32 v5, 1.0, v5
	v_div_scale_f32 v144, s[20:21], v6, v6, 1.0
	v_rcp_f32_e32 v145, v144
	v_div_scale_f32 v146, vcc, 1.0, v6, 1.0
	v_fma_f32 v147, -v144, v145, 1.0
	v_fmac_f32_e32 v145, v147, v145
	v_mul_f32_e32 v147, v146, v145
	v_fma_f32 v148, -v144, v147, v146
	v_fmac_f32_e32 v147, v148, v145
	v_fma_f32 v144, -v144, v147, v146
	v_div_fmas_f32 v144, v144, v145, v147
	v_div_fixup_f32 v6, v144, v6, 1.0
	v_div_scale_f32 v144, s[20:21], v7, v7, 1.0
	v_rcp_f32_e32 v145, v144
	v_div_scale_f32 v146, vcc, 1.0, v7, 1.0
	v_fma_f32 v147, -v144, v145, 1.0
	v_fmac_f32_e32 v145, v147, v145
	v_mul_f32_e32 v147, v146, v145
	v_fma_f32 v148, -v144, v147, v146
	v_fmac_f32_e32 v147, v148, v145
	v_fma_f32 v144, -v144, v147, v146
	v_div_fmas_f32 v144, v144, v145, v147
	v_div_fixup_f32 v7, v144, v7, 1.0
	v_div_scale_f32 v144, s[20:21], v8, v8, 1.0
	v_rcp_f32_e32 v145, v144
	v_div_scale_f32 v146, vcc, 1.0, v8, 1.0
	v_fma_f32 v147, -v144, v145, 1.0
	v_fmac_f32_e32 v145, v147, v145
	v_mul_f32_e32 v147, v146, v145
	v_fma_f32 v148, -v144, v147, v146
	v_fmac_f32_e32 v147, v148, v145
	v_fma_f32 v144, -v144, v147, v146
	v_div_fmas_f32 v144, v144, v145, v147
	v_div_fixup_f32 v8, v144, v8, 1.0
	v_div_scale_f32 v144, s[20:21], v9, v9, 1.0
	v_rcp_f32_e32 v145, v144
	v_div_scale_f32 v146, vcc, 1.0, v9, 1.0
	v_fma_f32 v147, -v144, v145, 1.0
	v_fmac_f32_e32 v145, v147, v145
	v_mul_f32_e32 v147, v146, v145
	v_fma_f32 v148, -v144, v147, v146
	v_fmac_f32_e32 v147, v148, v145
	v_fma_f32 v144, -v144, v147, v146
	v_div_fmas_f32 v144, v144, v145, v147
	v_div_fixup_f32 v9, v144, v9, 1.0
	v_div_scale_f32 v144, s[20:21], v2, v2, 1.0
	v_rcp_f32_e32 v145, v144
	v_div_scale_f32 v146, vcc, 1.0, v2, 1.0
	v_fma_f32 v147, -v144, v145, 1.0
	v_fmac_f32_e32 v145, v147, v145
	v_mul_f32_e32 v147, v146, v145
	v_fma_f32 v148, -v144, v147, v146
	v_fmac_f32_e32 v147, v148, v145
	v_fma_f32 v144, -v144, v147, v146
	v_div_fmas_f32 v144, v144, v145, v147
	v_div_fixup_f32 v2, v144, v2, 1.0
	v_div_scale_f32 v144, s[20:21], v3, v3, 1.0
	v_rcp_f32_e32 v145, v144
	v_div_scale_f32 v146, vcc, 1.0, v3, 1.0
	v_fma_f32 v147, -v144, v145, 1.0
	v_fmac_f32_e32 v145, v147, v145
	v_mul_f32_e32 v147, v146, v145
	v_fma_f32 v148, -v144, v147, v146
	v_fmac_f32_e32 v147, v148, v145
	v_fma_f32 v144, -v144, v147, v146
	v_div_fmas_f32 v144, v144, v145, v147
	v_div_fixup_f32 v3, v144, v3, 1.0
	v_div_scale_f32 v144, s[20:21], v4, v4, 1.0
	v_rcp_f32_e32 v145, v144
	v_div_scale_f32 v146, vcc, 1.0, v4, 1.0
	v_fma_f32 v147, -v144, v145, 1.0
	v_fmac_f32_e32 v145, v147, v145
	v_mul_f32_e32 v147, v146, v145
	v_fma_f32 v148, -v144, v147, v146
	v_fmac_f32_e32 v147, v148, v145
	v_fma_f32 v144, -v144, v147, v146
	v_div_fmas_f32 v144, v144, v145, v147
	v_div_fixup_f32 v4, v144, v4, 1.0
	v_div_scale_f32 v144, s[20:21], v5, v5, 1.0
	v_rcp_f32_e32 v145, v144
	v_div_scale_f32 v146, vcc, 1.0, v5, 1.0
	v_fma_f32 v147, -v144, v145, 1.0
	v_fmac_f32_e32 v145, v147, v145
	v_mul_f32_e32 v147, v146, v145
	v_fma_f32 v148, -v144, v147, v146
	v_fmac_f32_e32 v147, v148, v145
	v_fma_f32 v144, -v144, v147, v146
	v_div_fmas_f32 v144, v144, v145, v147
	v_div_fixup_f32 v5, v144, v5, 1.0
	v_cvt_pk_bf16_f32 v6, v6, v7
	v_cvt_pk_bf16_f32 v7, v8, v9
	v_cvt_pk_bf16_f32 v8, v2, v3
	v_cvt_pk_bf16_f32 v9, v4, v5
	global_store_dwordx4 v156, v[6:9], s[44:45]
	v_pk_add_f32 v[134:135], v[134:135], v[10:11]
	v_pk_add_f32 v[136:137], v[136:137], v[12:13]
	v_pk_add_f32 v[130:131], v[130:131], v[14:15]
	v_pk_add_f32 v[132:133], v[132:133], v[16:17]
	v_mul_f32_e32 v134, 0xbfb8aa3b, v134
	v_mul_f32_e32 v135, 0xbfb8aa3b, v135
	v_mul_f32_e32 v136, 0xbfb8aa3b, v136
	v_mul_f32_e32 v137, 0xbfb8aa3b, v137
	v_mul_f32_e32 v130, 0xbfb8aa3b, v130
	v_mul_f32_e32 v131, 0xbfb8aa3b, v131
	v_mul_f32_e32 v132, 0xbfb8aa3b, v132
	v_mul_f32_e32 v133, 0xbfb8aa3b, v133
	v_exp_f32_e32 v134, v134
	v_exp_f32_e32 v135, v135
	v_exp_f32_e32 v136, v136
	v_exp_f32_e32 v137, v137
	v_exp_f32_e32 v130, v130
	v_exp_f32_e32 v131, v131
	v_exp_f32_e32 v132, v132
	v_exp_f32_e32 v133, v133
	v_add_f32_e32 v134, 1.0, v134
	v_add_f32_e32 v135, 1.0, v135
	v_add_f32_e32 v136, 1.0, v136
	v_add_f32_e32 v137, 1.0, v137
	v_add_f32_e32 v130, 1.0, v130
	v_add_f32_e32 v131, 1.0, v131
	v_add_f32_e32 v132, 1.0, v132
	v_add_f32_e32 v133, 1.0, v133
	v_div_scale_f32 v144, s[20:21], v134, v134, 1.0
	v_rcp_f32_e32 v145, v144
	v_div_scale_f32 v146, vcc, 1.0, v134, 1.0
	v_fma_f32 v147, -v144, v145, 1.0
	v_fmac_f32_e32 v145, v147, v145
	v_mul_f32_e32 v147, v146, v145
	v_fma_f32 v148, -v144, v147, v146
	v_fmac_f32_e32 v147, v148, v145
	v_fma_f32 v144, -v144, v147, v146
	v_div_fmas_f32 v144, v144, v145, v147
	v_div_fixup_f32 v134, v144, v134, 1.0
	v_div_scale_f32 v144, s[20:21], v135, v135, 1.0
	v_rcp_f32_e32 v145, v144
	v_div_scale_f32 v146, vcc, 1.0, v135, 1.0
	v_fma_f32 v147, -v144, v145, 1.0
	v_fmac_f32_e32 v145, v147, v145
	v_mul_f32_e32 v147, v146, v145
	v_fma_f32 v148, -v144, v147, v146
	v_fmac_f32_e32 v147, v148, v145
	v_fma_f32 v144, -v144, v147, v146
	v_div_fmas_f32 v144, v144, v145, v147
	v_div_fixup_f32 v135, v144, v135, 1.0
	v_div_scale_f32 v144, s[20:21], v136, v136, 1.0
	v_rcp_f32_e32 v145, v144
	v_div_scale_f32 v146, vcc, 1.0, v136, 1.0
	v_fma_f32 v147, -v144, v145, 1.0
	v_fmac_f32_e32 v145, v147, v145
	v_mul_f32_e32 v147, v146, v145
	v_fma_f32 v148, -v144, v147, v146
	v_fmac_f32_e32 v147, v148, v145
	v_fma_f32 v144, -v144, v147, v146
	v_div_fmas_f32 v144, v144, v145, v147
	v_div_fixup_f32 v136, v144, v136, 1.0
	v_div_scale_f32 v144, s[20:21], v137, v137, 1.0
	v_rcp_f32_e32 v145, v144
	v_div_scale_f32 v146, vcc, 1.0, v137, 1.0
	v_fma_f32 v147, -v144, v145, 1.0
	v_fmac_f32_e32 v145, v147, v145
	v_mul_f32_e32 v147, v146, v145
	v_fma_f32 v148, -v144, v147, v146
	v_fmac_f32_e32 v147, v148, v145
	v_fma_f32 v144, -v144, v147, v146
	v_div_fmas_f32 v144, v144, v145, v147
	v_div_fixup_f32 v137, v144, v137, 1.0
	v_div_scale_f32 v144, s[20:21], v130, v130, 1.0
	v_rcp_f32_e32 v145, v144
	v_div_scale_f32 v146, vcc, 1.0, v130, 1.0
	v_fma_f32 v147, -v144, v145, 1.0
	v_fmac_f32_e32 v145, v147, v145
	v_mul_f32_e32 v147, v146, v145
	v_fma_f32 v148, -v144, v147, v146
	v_fmac_f32_e32 v147, v148, v145
	v_fma_f32 v144, -v144, v147, v146
	v_div_fmas_f32 v144, v144, v145, v147
	v_div_fixup_f32 v130, v144, v130, 1.0
	v_div_scale_f32 v144, s[20:21], v131, v131, 1.0
	v_rcp_f32_e32 v145, v144
	v_div_scale_f32 v146, vcc, 1.0, v131, 1.0
	v_fma_f32 v147, -v144, v145, 1.0
	v_fmac_f32_e32 v145, v147, v145
	v_mul_f32_e32 v147, v146, v145
	v_fma_f32 v148, -v144, v147, v146
	v_fmac_f32_e32 v147, v148, v145
	v_fma_f32 v144, -v144, v147, v146
	v_div_fmas_f32 v144, v144, v145, v147
	v_div_fixup_f32 v131, v144, v131, 1.0
	v_div_scale_f32 v144, s[20:21], v132, v132, 1.0
	v_rcp_f32_e32 v145, v144
	v_div_scale_f32 v146, vcc, 1.0, v132, 1.0
	v_fma_f32 v147, -v144, v145, 1.0
	v_fmac_f32_e32 v145, v147, v145
	v_mul_f32_e32 v147, v146, v145
	v_fma_f32 v148, -v144, v147, v146
	v_fmac_f32_e32 v147, v148, v145
	v_fma_f32 v144, -v144, v147, v146
	v_div_fmas_f32 v144, v144, v145, v147
	v_div_fixup_f32 v132, v144, v132, 1.0
	v_div_scale_f32 v144, s[20:21], v133, v133, 1.0
	v_rcp_f32_e32 v145, v144
	v_div_scale_f32 v146, vcc, 1.0, v133, 1.0
	v_fma_f32 v147, -v144, v145, 1.0
	v_fmac_f32_e32 v145, v147, v145
	v_mul_f32_e32 v147, v146, v145
	v_fma_f32 v148, -v144, v147, v146
	v_fmac_f32_e32 v147, v148, v145
	v_fma_f32 v144, -v144, v147, v146
	v_div_fmas_f32 v144, v144, v145, v147
	v_div_fixup_f32 v133, v144, v133, 1.0
	v_cvt_pk_bf16_f32 v134, v134, v135
	v_cvt_pk_bf16_f32 v135, v136, v137
	v_cvt_pk_bf16_f32 v136, v130, v131
	v_cvt_pk_bf16_f32 v137, v132, v133
	v_add_u32_e32 v157, 0x10000, v156
	global_store_dwordx4 v157, v[134:137], s[44:45]
	v_pk_add_f32 v[126:127], v[126:127], v[10:11]
	v_pk_add_f32 v[128:129], v[128:129], v[12:13]
	v_pk_add_f32 v[122:123], v[122:123], v[14:15]
	v_pk_add_f32 v[124:125], v[124:125], v[16:17]
	v_mul_f32_e32 v126, 0xbfb8aa3b, v126
	v_mul_f32_e32 v127, 0xbfb8aa3b, v127
	v_mul_f32_e32 v128, 0xbfb8aa3b, v128
	v_mul_f32_e32 v129, 0xbfb8aa3b, v129
	v_mul_f32_e32 v122, 0xbfb8aa3b, v122
	v_mul_f32_e32 v123, 0xbfb8aa3b, v123
	v_mul_f32_e32 v124, 0xbfb8aa3b, v124
	v_mul_f32_e32 v125, 0xbfb8aa3b, v125
	v_exp_f32_e32 v126, v126
	v_exp_f32_e32 v127, v127
	v_exp_f32_e32 v128, v128
	v_exp_f32_e32 v129, v129
	v_exp_f32_e32 v122, v122
	v_exp_f32_e32 v123, v123
	v_exp_f32_e32 v124, v124
	v_exp_f32_e32 v125, v125
	v_add_f32_e32 v126, 1.0, v126
	v_add_f32_e32 v127, 1.0, v127
	v_add_f32_e32 v128, 1.0, v128
	v_add_f32_e32 v129, 1.0, v129
	v_add_f32_e32 v122, 1.0, v122
	v_add_f32_e32 v123, 1.0, v123
	v_add_f32_e32 v124, 1.0, v124
	v_add_f32_e32 v125, 1.0, v125
	v_div_scale_f32 v144, s[20:21], v126, v126, 1.0
	v_rcp_f32_e32 v145, v144
	v_div_scale_f32 v146, vcc, 1.0, v126, 1.0
	v_fma_f32 v147, -v144, v145, 1.0
	v_fmac_f32_e32 v145, v147, v145
	v_mul_f32_e32 v147, v146, v145
	v_fma_f32 v148, -v144, v147, v146
	v_fmac_f32_e32 v147, v148, v145
	v_fma_f32 v144, -v144, v147, v146
	v_div_fmas_f32 v144, v144, v145, v147
	v_div_fixup_f32 v126, v144, v126, 1.0
	v_div_scale_f32 v144, s[20:21], v127, v127, 1.0
	v_rcp_f32_e32 v145, v144
	v_div_scale_f32 v146, vcc, 1.0, v127, 1.0
	v_fma_f32 v147, -v144, v145, 1.0
	v_fmac_f32_e32 v145, v147, v145
	v_mul_f32_e32 v147, v146, v145
	v_fma_f32 v148, -v144, v147, v146
	v_fmac_f32_e32 v147, v148, v145
	v_fma_f32 v144, -v144, v147, v146
	v_div_fmas_f32 v144, v144, v145, v147
	v_div_fixup_f32 v127, v144, v127, 1.0
	v_div_scale_f32 v144, s[20:21], v128, v128, 1.0
	v_rcp_f32_e32 v145, v144
	v_div_scale_f32 v146, vcc, 1.0, v128, 1.0
	v_fma_f32 v147, -v144, v145, 1.0
	v_fmac_f32_e32 v145, v147, v145
	v_mul_f32_e32 v147, v146, v145
	v_fma_f32 v148, -v144, v147, v146
	v_fmac_f32_e32 v147, v148, v145
	v_fma_f32 v144, -v144, v147, v146
	v_div_fmas_f32 v144, v144, v145, v147
	v_div_fixup_f32 v128, v144, v128, 1.0
	v_div_scale_f32 v144, s[20:21], v129, v129, 1.0
	v_rcp_f32_e32 v145, v144
	v_div_scale_f32 v146, vcc, 1.0, v129, 1.0
	v_fma_f32 v147, -v144, v145, 1.0
	v_fmac_f32_e32 v145, v147, v145
	v_mul_f32_e32 v147, v146, v145
	v_fma_f32 v148, -v144, v147, v146
	v_fmac_f32_e32 v147, v148, v145
	v_fma_f32 v144, -v144, v147, v146
	v_div_fmas_f32 v144, v144, v145, v147
	v_div_fixup_f32 v129, v144, v129, 1.0
	v_div_scale_f32 v144, s[20:21], v122, v122, 1.0
	v_rcp_f32_e32 v145, v144
	v_div_scale_f32 v146, vcc, 1.0, v122, 1.0
	v_fma_f32 v147, -v144, v145, 1.0
	v_fmac_f32_e32 v145, v147, v145
	v_mul_f32_e32 v147, v146, v145
	v_fma_f32 v148, -v144, v147, v146
	v_fmac_f32_e32 v147, v148, v145
	v_fma_f32 v144, -v144, v147, v146
	v_div_fmas_f32 v144, v144, v145, v147
	v_div_fixup_f32 v122, v144, v122, 1.0
	v_div_scale_f32 v144, s[20:21], v123, v123, 1.0
	v_rcp_f32_e32 v145, v144
	v_div_scale_f32 v146, vcc, 1.0, v123, 1.0
	v_fma_f32 v147, -v144, v145, 1.0
	v_fmac_f32_e32 v145, v147, v145
	v_mul_f32_e32 v147, v146, v145
	v_fma_f32 v148, -v144, v147, v146
	v_fmac_f32_e32 v147, v148, v145
	v_fma_f32 v144, -v144, v147, v146
	v_div_fmas_f32 v144, v144, v145, v147
	v_div_fixup_f32 v123, v144, v123, 1.0
	v_div_scale_f32 v144, s[20:21], v124, v124, 1.0
	v_rcp_f32_e32 v145, v144
	v_div_scale_f32 v146, vcc, 1.0, v124, 1.0
	v_fma_f32 v147, -v144, v145, 1.0
	v_fmac_f32_e32 v145, v147, v145
	v_mul_f32_e32 v147, v146, v145
	v_fma_f32 v148, -v144, v147, v146
	v_fmac_f32_e32 v147, v148, v145
	v_fma_f32 v144, -v144, v147, v146
	v_div_fmas_f32 v144, v144, v145, v147
	v_div_fixup_f32 v124, v144, v124, 1.0
	v_div_scale_f32 v144, s[20:21], v125, v125, 1.0
	v_rcp_f32_e32 v145, v144
	v_div_scale_f32 v146, vcc, 1.0, v125, 1.0
	v_fma_f32 v147, -v144, v145, 1.0
	v_fmac_f32_e32 v145, v147, v145
	v_mul_f32_e32 v147, v146, v145
	v_fma_f32 v148, -v144, v147, v146
	v_fmac_f32_e32 v147, v148, v145
	v_fma_f32 v144, -v144, v147, v146
	v_div_fmas_f32 v144, v144, v145, v147
	v_div_fixup_f32 v125, v144, v125, 1.0
	v_cvt_pk_bf16_f32 v126, v126, v127
	v_cvt_pk_bf16_f32 v127, v128, v129
	v_cvt_pk_bf16_f32 v128, v122, v123
	v_cvt_pk_bf16_f32 v129, v124, v125
	v_add_u32_e32 v157, 0x20000, v156
	global_store_dwordx4 v157, v[126:129], s[44:45]
	v_pk_add_f32 v[118:119], v[118:119], v[10:11]
	v_pk_add_f32 v[120:121], v[120:121], v[12:13]
	v_pk_add_f32 v[114:115], v[114:115], v[14:15]
	v_pk_add_f32 v[116:117], v[116:117], v[16:17]
	v_mul_f32_e32 v118, 0xbfb8aa3b, v118
	v_mul_f32_e32 v119, 0xbfb8aa3b, v119
	v_mul_f32_e32 v120, 0xbfb8aa3b, v120
	v_mul_f32_e32 v121, 0xbfb8aa3b, v121
	v_mul_f32_e32 v114, 0xbfb8aa3b, v114
	v_mul_f32_e32 v115, 0xbfb8aa3b, v115
	v_mul_f32_e32 v116, 0xbfb8aa3b, v116
	v_mul_f32_e32 v117, 0xbfb8aa3b, v117
	v_exp_f32_e32 v118, v118
	v_exp_f32_e32 v119, v119
	v_exp_f32_e32 v120, v120
	v_exp_f32_e32 v121, v121
	v_exp_f32_e32 v114, v114
	v_exp_f32_e32 v115, v115
	v_exp_f32_e32 v116, v116
	v_exp_f32_e32 v117, v117
	v_add_f32_e32 v118, 1.0, v118
	v_add_f32_e32 v119, 1.0, v119
	v_add_f32_e32 v120, 1.0, v120
	v_add_f32_e32 v121, 1.0, v121
	v_add_f32_e32 v114, 1.0, v114
	v_add_f32_e32 v115, 1.0, v115
	v_add_f32_e32 v116, 1.0, v116
	v_add_f32_e32 v117, 1.0, v117
	v_div_scale_f32 v144, s[20:21], v118, v118, 1.0
	v_rcp_f32_e32 v145, v144
	v_div_scale_f32 v146, vcc, 1.0, v118, 1.0
	v_fma_f32 v147, -v144, v145, 1.0
	v_fmac_f32_e32 v145, v147, v145
	v_mul_f32_e32 v147, v146, v145
	v_fma_f32 v148, -v144, v147, v146
	v_fmac_f32_e32 v147, v148, v145
	v_fma_f32 v144, -v144, v147, v146
	v_div_fmas_f32 v144, v144, v145, v147
	v_div_fixup_f32 v118, v144, v118, 1.0
	v_div_scale_f32 v144, s[20:21], v119, v119, 1.0
	v_rcp_f32_e32 v145, v144
	v_div_scale_f32 v146, vcc, 1.0, v119, 1.0
	v_fma_f32 v147, -v144, v145, 1.0
	v_fmac_f32_e32 v145, v147, v145
	v_mul_f32_e32 v147, v146, v145
	v_fma_f32 v148, -v144, v147, v146
	v_fmac_f32_e32 v147, v148, v145
	v_fma_f32 v144, -v144, v147, v146
	v_div_fmas_f32 v144, v144, v145, v147
	v_div_fixup_f32 v119, v144, v119, 1.0
	v_div_scale_f32 v144, s[20:21], v120, v120, 1.0
	v_rcp_f32_e32 v145, v144
	v_div_scale_f32 v146, vcc, 1.0, v120, 1.0
	v_fma_f32 v147, -v144, v145, 1.0
	v_fmac_f32_e32 v145, v147, v145
	v_mul_f32_e32 v147, v146, v145
	v_fma_f32 v148, -v144, v147, v146
	v_fmac_f32_e32 v147, v148, v145
	v_fma_f32 v144, -v144, v147, v146
	v_div_fmas_f32 v144, v144, v145, v147
	v_div_fixup_f32 v120, v144, v120, 1.0
	v_div_scale_f32 v144, s[20:21], v121, v121, 1.0
	v_rcp_f32_e32 v145, v144
	v_div_scale_f32 v146, vcc, 1.0, v121, 1.0
	v_fma_f32 v147, -v144, v145, 1.0
	v_fmac_f32_e32 v145, v147, v145
	v_mul_f32_e32 v147, v146, v145
	v_fma_f32 v148, -v144, v147, v146
	v_fmac_f32_e32 v147, v148, v145
	v_fma_f32 v144, -v144, v147, v146
	v_div_fmas_f32 v144, v144, v145, v147
	v_div_fixup_f32 v121, v144, v121, 1.0
	v_div_scale_f32 v144, s[20:21], v114, v114, 1.0
	v_rcp_f32_e32 v145, v144
	v_div_scale_f32 v146, vcc, 1.0, v114, 1.0
	v_fma_f32 v147, -v144, v145, 1.0
	v_fmac_f32_e32 v145, v147, v145
	v_mul_f32_e32 v147, v146, v145
	v_fma_f32 v148, -v144, v147, v146
	v_fmac_f32_e32 v147, v148, v145
	v_fma_f32 v144, -v144, v147, v146
	v_div_fmas_f32 v144, v144, v145, v147
	v_div_fixup_f32 v114, v144, v114, 1.0
	v_div_scale_f32 v144, s[20:21], v115, v115, 1.0
	v_rcp_f32_e32 v145, v144
	v_div_scale_f32 v146, vcc, 1.0, v115, 1.0
	v_fma_f32 v147, -v144, v145, 1.0
	v_fmac_f32_e32 v145, v147, v145
	v_mul_f32_e32 v147, v146, v145
	v_fma_f32 v148, -v144, v147, v146
	v_fmac_f32_e32 v147, v148, v145
	v_fma_f32 v144, -v144, v147, v146
	v_div_fmas_f32 v144, v144, v145, v147
	v_div_fixup_f32 v115, v144, v115, 1.0
	v_div_scale_f32 v144, s[20:21], v116, v116, 1.0
	v_rcp_f32_e32 v145, v144
	v_div_scale_f32 v146, vcc, 1.0, v116, 1.0
	v_fma_f32 v147, -v144, v145, 1.0
	v_fmac_f32_e32 v145, v147, v145
	v_mul_f32_e32 v147, v146, v145
	v_fma_f32 v148, -v144, v147, v146
	v_fmac_f32_e32 v147, v148, v145
	v_fma_f32 v144, -v144, v147, v146
	v_div_fmas_f32 v144, v144, v145, v147
	v_div_fixup_f32 v116, v144, v116, 1.0
	v_div_scale_f32 v144, s[20:21], v117, v117, 1.0
	v_rcp_f32_e32 v145, v144
	v_div_scale_f32 v146, vcc, 1.0, v117, 1.0
	v_fma_f32 v147, -v144, v145, 1.0
	v_fmac_f32_e32 v145, v147, v145
	v_mul_f32_e32 v147, v146, v145
	v_fma_f32 v148, -v144, v147, v146
	v_fmac_f32_e32 v147, v148, v145
	v_fma_f32 v144, -v144, v147, v146
	v_div_fmas_f32 v144, v144, v145, v147
	v_div_fixup_f32 v117, v144, v117, 1.0
	v_cvt_pk_bf16_f32 v118, v118, v119
	v_cvt_pk_bf16_f32 v119, v120, v121
	v_cvt_pk_bf16_f32 v120, v114, v115
	v_cvt_pk_bf16_f32 v121, v116, v117
	v_add_u32_e32 v157, 0x30000, v156
	global_store_dwordx4 v157, v[118:121], s[44:45]
	v_pk_add_f32 v[110:111], v[110:111], v[10:11]
	v_pk_add_f32 v[112:113], v[112:113], v[12:13]
	v_pk_add_f32 v[106:107], v[106:107], v[14:15]
	v_pk_add_f32 v[108:109], v[108:109], v[16:17]
	v_mul_f32_e32 v110, 0xbfb8aa3b, v110
	v_mul_f32_e32 v111, 0xbfb8aa3b, v111
	v_mul_f32_e32 v112, 0xbfb8aa3b, v112
	v_mul_f32_e32 v113, 0xbfb8aa3b, v113
	v_mul_f32_e32 v106, 0xbfb8aa3b, v106
	v_mul_f32_e32 v107, 0xbfb8aa3b, v107
	v_mul_f32_e32 v108, 0xbfb8aa3b, v108
	v_mul_f32_e32 v109, 0xbfb8aa3b, v109
	v_exp_f32_e32 v110, v110
	v_exp_f32_e32 v111, v111
	v_exp_f32_e32 v112, v112
	v_exp_f32_e32 v113, v113
	v_exp_f32_e32 v106, v106
	v_exp_f32_e32 v107, v107
	v_exp_f32_e32 v108, v108
	v_exp_f32_e32 v109, v109
	v_add_f32_e32 v110, 1.0, v110
	v_add_f32_e32 v111, 1.0, v111
	v_add_f32_e32 v112, 1.0, v112
	v_add_f32_e32 v113, 1.0, v113
	v_add_f32_e32 v106, 1.0, v106
	v_add_f32_e32 v107, 1.0, v107
	v_add_f32_e32 v108, 1.0, v108
	v_add_f32_e32 v109, 1.0, v109
	v_div_scale_f32 v144, s[20:21], v110, v110, 1.0
	v_rcp_f32_e32 v145, v144
	v_div_scale_f32 v146, vcc, 1.0, v110, 1.0
	v_fma_f32 v147, -v144, v145, 1.0
	v_fmac_f32_e32 v145, v147, v145
	v_mul_f32_e32 v147, v146, v145
	v_fma_f32 v148, -v144, v147, v146
	v_fmac_f32_e32 v147, v148, v145
	v_fma_f32 v144, -v144, v147, v146
	v_div_fmas_f32 v144, v144, v145, v147
	v_div_fixup_f32 v110, v144, v110, 1.0
	v_div_scale_f32 v144, s[20:21], v111, v111, 1.0
	v_rcp_f32_e32 v145, v144
	v_div_scale_f32 v146, vcc, 1.0, v111, 1.0
	v_fma_f32 v147, -v144, v145, 1.0
	v_fmac_f32_e32 v145, v147, v145
	v_mul_f32_e32 v147, v146, v145
	v_fma_f32 v148, -v144, v147, v146
	v_fmac_f32_e32 v147, v148, v145
	v_fma_f32 v144, -v144, v147, v146
	v_div_fmas_f32 v144, v144, v145, v147
	v_div_fixup_f32 v111, v144, v111, 1.0
	v_div_scale_f32 v144, s[20:21], v112, v112, 1.0
	v_rcp_f32_e32 v145, v144
	v_div_scale_f32 v146, vcc, 1.0, v112, 1.0
	v_fma_f32 v147, -v144, v145, 1.0
	v_fmac_f32_e32 v145, v147, v145
	v_mul_f32_e32 v147, v146, v145
	v_fma_f32 v148, -v144, v147, v146
	v_fmac_f32_e32 v147, v148, v145
	v_fma_f32 v144, -v144, v147, v146
	v_div_fmas_f32 v144, v144, v145, v147
	v_div_fixup_f32 v112, v144, v112, 1.0
	v_div_scale_f32 v144, s[20:21], v113, v113, 1.0
	v_rcp_f32_e32 v145, v144
	v_div_scale_f32 v146, vcc, 1.0, v113, 1.0
	v_fma_f32 v147, -v144, v145, 1.0
	v_fmac_f32_e32 v145, v147, v145
	v_mul_f32_e32 v147, v146, v145
	v_fma_f32 v148, -v144, v147, v146
	v_fmac_f32_e32 v147, v148, v145
	v_fma_f32 v144, -v144, v147, v146
	v_div_fmas_f32 v144, v144, v145, v147
	v_div_fixup_f32 v113, v144, v113, 1.0
	v_div_scale_f32 v144, s[20:21], v106, v106, 1.0
	v_rcp_f32_e32 v145, v144
	v_div_scale_f32 v146, vcc, 1.0, v106, 1.0
	v_fma_f32 v147, -v144, v145, 1.0
	v_fmac_f32_e32 v145, v147, v145
	v_mul_f32_e32 v147, v146, v145
	v_fma_f32 v148, -v144, v147, v146
	v_fmac_f32_e32 v147, v148, v145
	v_fma_f32 v144, -v144, v147, v146
	v_div_fmas_f32 v144, v144, v145, v147
	v_div_fixup_f32 v106, v144, v106, 1.0
	v_div_scale_f32 v144, s[20:21], v107, v107, 1.0
	v_rcp_f32_e32 v145, v144
	v_div_scale_f32 v146, vcc, 1.0, v107, 1.0
	v_fma_f32 v147, -v144, v145, 1.0
	v_fmac_f32_e32 v145, v147, v145
	v_mul_f32_e32 v147, v146, v145
	v_fma_f32 v148, -v144, v147, v146
	v_fmac_f32_e32 v147, v148, v145
	v_fma_f32 v144, -v144, v147, v146
	v_div_fmas_f32 v144, v144, v145, v147
	v_div_fixup_f32 v107, v144, v107, 1.0
	v_div_scale_f32 v144, s[20:21], v108, v108, 1.0
	v_rcp_f32_e32 v145, v144
	v_div_scale_f32 v146, vcc, 1.0, v108, 1.0
	v_fma_f32 v147, -v144, v145, 1.0
	v_fmac_f32_e32 v145, v147, v145
	v_mul_f32_e32 v147, v146, v145
	v_fma_f32 v148, -v144, v147, v146
	v_fmac_f32_e32 v147, v148, v145
	v_fma_f32 v144, -v144, v147, v146
	v_div_fmas_f32 v144, v144, v145, v147
	v_div_fixup_f32 v108, v144, v108, 1.0
	v_div_scale_f32 v144, s[20:21], v109, v109, 1.0
	v_rcp_f32_e32 v145, v144
	v_div_scale_f32 v146, vcc, 1.0, v109, 1.0
	v_fma_f32 v147, -v144, v145, 1.0
	v_fmac_f32_e32 v145, v147, v145
	v_mul_f32_e32 v147, v146, v145
	v_fma_f32 v148, -v144, v147, v146
	v_fmac_f32_e32 v147, v148, v145
	v_fma_f32 v144, -v144, v147, v146
	v_div_fmas_f32 v144, v144, v145, v147
	v_div_fixup_f32 v109, v144, v109, 1.0
	v_cvt_pk_bf16_f32 v110, v110, v111
	v_cvt_pk_bf16_f32 v111, v112, v113
	v_cvt_pk_bf16_f32 v112, v106, v107
	v_cvt_pk_bf16_f32 v113, v108, v109
	v_add_u32_e32 v157, 0x80000, v156
	global_store_dwordx4 v157, v[110:113], s[44:45]
	v_pk_add_f32 v[102:103], v[102:103], v[10:11]
	v_pk_add_f32 v[104:105], v[104:105], v[12:13]
	v_pk_add_f32 v[98:99], v[98:99], v[14:15]
	v_pk_add_f32 v[100:101], v[100:101], v[16:17]
	v_mul_f32_e32 v102, 0xbfb8aa3b, v102
	v_mul_f32_e32 v103, 0xbfb8aa3b, v103
	v_mul_f32_e32 v104, 0xbfb8aa3b, v104
	v_mul_f32_e32 v105, 0xbfb8aa3b, v105
	v_mul_f32_e32 v98, 0xbfb8aa3b, v98
	v_mul_f32_e32 v99, 0xbfb8aa3b, v99
	v_mul_f32_e32 v100, 0xbfb8aa3b, v100
	v_mul_f32_e32 v101, 0xbfb8aa3b, v101
	v_exp_f32_e32 v102, v102
	v_exp_f32_e32 v103, v103
	v_exp_f32_e32 v104, v104
	v_exp_f32_e32 v105, v105
	v_exp_f32_e32 v98, v98
	v_exp_f32_e32 v99, v99
	v_exp_f32_e32 v100, v100
	v_exp_f32_e32 v101, v101
	v_add_f32_e32 v102, 1.0, v102
	v_add_f32_e32 v103, 1.0, v103
	v_add_f32_e32 v104, 1.0, v104
	v_add_f32_e32 v105, 1.0, v105
	v_add_f32_e32 v98, 1.0, v98
	v_add_f32_e32 v99, 1.0, v99
	v_add_f32_e32 v100, 1.0, v100
	v_add_f32_e32 v101, 1.0, v101
	v_div_scale_f32 v144, s[20:21], v102, v102, 1.0
	v_rcp_f32_e32 v145, v144
	v_div_scale_f32 v146, vcc, 1.0, v102, 1.0
	v_fma_f32 v147, -v144, v145, 1.0
	v_fmac_f32_e32 v145, v147, v145
	v_mul_f32_e32 v147, v146, v145
	v_fma_f32 v148, -v144, v147, v146
	v_fmac_f32_e32 v147, v148, v145
	v_fma_f32 v144, -v144, v147, v146
	v_div_fmas_f32 v144, v144, v145, v147
	v_div_fixup_f32 v102, v144, v102, 1.0
	v_div_scale_f32 v144, s[20:21], v103, v103, 1.0
	v_rcp_f32_e32 v145, v144
	v_div_scale_f32 v146, vcc, 1.0, v103, 1.0
	v_fma_f32 v147, -v144, v145, 1.0
	v_fmac_f32_e32 v145, v147, v145
	v_mul_f32_e32 v147, v146, v145
	v_fma_f32 v148, -v144, v147, v146
	v_fmac_f32_e32 v147, v148, v145
	v_fma_f32 v144, -v144, v147, v146
	v_div_fmas_f32 v144, v144, v145, v147
	v_div_fixup_f32 v103, v144, v103, 1.0
	v_div_scale_f32 v144, s[20:21], v104, v104, 1.0
	v_rcp_f32_e32 v145, v144
	v_div_scale_f32 v146, vcc, 1.0, v104, 1.0
	v_fma_f32 v147, -v144, v145, 1.0
	v_fmac_f32_e32 v145, v147, v145
	v_mul_f32_e32 v147, v146, v145
	v_fma_f32 v148, -v144, v147, v146
	v_fmac_f32_e32 v147, v148, v145
	v_fma_f32 v144, -v144, v147, v146
	v_div_fmas_f32 v144, v144, v145, v147
	v_div_fixup_f32 v104, v144, v104, 1.0
	v_div_scale_f32 v144, s[20:21], v105, v105, 1.0
	v_rcp_f32_e32 v145, v144
	v_div_scale_f32 v146, vcc, 1.0, v105, 1.0
	v_fma_f32 v147, -v144, v145, 1.0
	v_fmac_f32_e32 v145, v147, v145
	v_mul_f32_e32 v147, v146, v145
	v_fma_f32 v148, -v144, v147, v146
	v_fmac_f32_e32 v147, v148, v145
	v_fma_f32 v144, -v144, v147, v146
	v_div_fmas_f32 v144, v144, v145, v147
	v_div_fixup_f32 v105, v144, v105, 1.0
	v_div_scale_f32 v144, s[20:21], v98, v98, 1.0
	v_rcp_f32_e32 v145, v144
	v_div_scale_f32 v146, vcc, 1.0, v98, 1.0
	v_fma_f32 v147, -v144, v145, 1.0
	v_fmac_f32_e32 v145, v147, v145
	v_mul_f32_e32 v147, v146, v145
	v_fma_f32 v148, -v144, v147, v146
	v_fmac_f32_e32 v147, v148, v145
	v_fma_f32 v144, -v144, v147, v146
	v_div_fmas_f32 v144, v144, v145, v147
	v_div_fixup_f32 v98, v144, v98, 1.0
	v_div_scale_f32 v144, s[20:21], v99, v99, 1.0
	v_rcp_f32_e32 v145, v144
	v_div_scale_f32 v146, vcc, 1.0, v99, 1.0
	v_fma_f32 v147, -v144, v145, 1.0
	v_fmac_f32_e32 v145, v147, v145
	v_mul_f32_e32 v147, v146, v145
	v_fma_f32 v148, -v144, v147, v146
	v_fmac_f32_e32 v147, v148, v145
	v_fma_f32 v144, -v144, v147, v146
	v_div_fmas_f32 v144, v144, v145, v147
	v_div_fixup_f32 v99, v144, v99, 1.0
	v_div_scale_f32 v144, s[20:21], v100, v100, 1.0
	v_rcp_f32_e32 v145, v144
	v_div_scale_f32 v146, vcc, 1.0, v100, 1.0
	v_fma_f32 v147, -v144, v145, 1.0
	v_fmac_f32_e32 v145, v147, v145
	v_mul_f32_e32 v147, v146, v145
	v_fma_f32 v148, -v144, v147, v146
	v_fmac_f32_e32 v147, v148, v145
	v_fma_f32 v144, -v144, v147, v146
	v_div_fmas_f32 v144, v144, v145, v147
	v_div_fixup_f32 v100, v144, v100, 1.0
	v_div_scale_f32 v144, s[20:21], v101, v101, 1.0
	v_rcp_f32_e32 v145, v144
	v_div_scale_f32 v146, vcc, 1.0, v101, 1.0
	v_fma_f32 v147, -v144, v145, 1.0
	v_fmac_f32_e32 v145, v147, v145
	v_mul_f32_e32 v147, v146, v145
	v_fma_f32 v148, -v144, v147, v146
	v_fmac_f32_e32 v147, v148, v145
	v_fma_f32 v144, -v144, v147, v146
	v_div_fmas_f32 v144, v144, v145, v147
	v_div_fixup_f32 v101, v144, v101, 1.0
	v_cvt_pk_bf16_f32 v102, v102, v103
	v_cvt_pk_bf16_f32 v103, v104, v105
	v_cvt_pk_bf16_f32 v104, v98, v99
	v_cvt_pk_bf16_f32 v105, v100, v101
	v_add_u32_e32 v157, 0x90000, v156
	global_store_dwordx4 v157, v[102:105], s[44:45]
	v_pk_add_f32 v[94:95], v[94:95], v[10:11]
	v_pk_add_f32 v[96:97], v[96:97], v[12:13]
	v_pk_add_f32 v[90:91], v[90:91], v[14:15]
	v_pk_add_f32 v[92:93], v[92:93], v[16:17]
	v_mul_f32_e32 v94, 0xbfb8aa3b, v94
	v_mul_f32_e32 v95, 0xbfb8aa3b, v95
	v_mul_f32_e32 v96, 0xbfb8aa3b, v96
	v_mul_f32_e32 v97, 0xbfb8aa3b, v97
	v_mul_f32_e32 v90, 0xbfb8aa3b, v90
	v_mul_f32_e32 v91, 0xbfb8aa3b, v91
	v_mul_f32_e32 v92, 0xbfb8aa3b, v92
	v_mul_f32_e32 v93, 0xbfb8aa3b, v93
	v_exp_f32_e32 v94, v94
	v_exp_f32_e32 v95, v95
	v_exp_f32_e32 v96, v96
	v_exp_f32_e32 v97, v97
	v_exp_f32_e32 v90, v90
	v_exp_f32_e32 v91, v91
	v_exp_f32_e32 v92, v92
	v_exp_f32_e32 v93, v93
	v_add_f32_e32 v94, 1.0, v94
	v_add_f32_e32 v95, 1.0, v95
	v_add_f32_e32 v96, 1.0, v96
	v_add_f32_e32 v97, 1.0, v97
	v_add_f32_e32 v90, 1.0, v90
	v_add_f32_e32 v91, 1.0, v91
	v_add_f32_e32 v92, 1.0, v92
	v_add_f32_e32 v93, 1.0, v93
	v_div_scale_f32 v144, s[20:21], v94, v94, 1.0
	v_rcp_f32_e32 v145, v144
	v_div_scale_f32 v146, vcc, 1.0, v94, 1.0
	v_fma_f32 v147, -v144, v145, 1.0
	v_fmac_f32_e32 v145, v147, v145
	v_mul_f32_e32 v147, v146, v145
	v_fma_f32 v148, -v144, v147, v146
	v_fmac_f32_e32 v147, v148, v145
	v_fma_f32 v144, -v144, v147, v146
	v_div_fmas_f32 v144, v144, v145, v147
	v_div_fixup_f32 v94, v144, v94, 1.0
	v_div_scale_f32 v144, s[20:21], v95, v95, 1.0
	v_rcp_f32_e32 v145, v144
	v_div_scale_f32 v146, vcc, 1.0, v95, 1.0
	v_fma_f32 v147, -v144, v145, 1.0
	v_fmac_f32_e32 v145, v147, v145
	v_mul_f32_e32 v147, v146, v145
	v_fma_f32 v148, -v144, v147, v146
	v_fmac_f32_e32 v147, v148, v145
	v_fma_f32 v144, -v144, v147, v146
	v_div_fmas_f32 v144, v144, v145, v147
	v_div_fixup_f32 v95, v144, v95, 1.0
	v_div_scale_f32 v144, s[20:21], v96, v96, 1.0
	v_rcp_f32_e32 v145, v144
	v_div_scale_f32 v146, vcc, 1.0, v96, 1.0
	v_fma_f32 v147, -v144, v145, 1.0
	v_fmac_f32_e32 v145, v147, v145
	v_mul_f32_e32 v147, v146, v145
	v_fma_f32 v148, -v144, v147, v146
	v_fmac_f32_e32 v147, v148, v145
	v_fma_f32 v144, -v144, v147, v146
	v_div_fmas_f32 v144, v144, v145, v147
	v_div_fixup_f32 v96, v144, v96, 1.0
	v_div_scale_f32 v144, s[20:21], v97, v97, 1.0
	v_rcp_f32_e32 v145, v144
	v_div_scale_f32 v146, vcc, 1.0, v97, 1.0
	v_fma_f32 v147, -v144, v145, 1.0
	v_fmac_f32_e32 v145, v147, v145
	v_mul_f32_e32 v147, v146, v145
	v_fma_f32 v148, -v144, v147, v146
	v_fmac_f32_e32 v147, v148, v145
	v_fma_f32 v144, -v144, v147, v146
	v_div_fmas_f32 v144, v144, v145, v147
	v_div_fixup_f32 v97, v144, v97, 1.0
	v_div_scale_f32 v144, s[20:21], v90, v90, 1.0
	v_rcp_f32_e32 v145, v144
	v_div_scale_f32 v146, vcc, 1.0, v90, 1.0
	v_fma_f32 v147, -v144, v145, 1.0
	v_fmac_f32_e32 v145, v147, v145
	v_mul_f32_e32 v147, v146, v145
	v_fma_f32 v148, -v144, v147, v146
	v_fmac_f32_e32 v147, v148, v145
	v_fma_f32 v144, -v144, v147, v146
	v_div_fmas_f32 v144, v144, v145, v147
	v_div_fixup_f32 v90, v144, v90, 1.0
	v_div_scale_f32 v144, s[20:21], v91, v91, 1.0
	v_rcp_f32_e32 v145, v144
	v_div_scale_f32 v146, vcc, 1.0, v91, 1.0
	v_fma_f32 v147, -v144, v145, 1.0
	v_fmac_f32_e32 v145, v147, v145
	v_mul_f32_e32 v147, v146, v145
	v_fma_f32 v148, -v144, v147, v146
	v_fmac_f32_e32 v147, v148, v145
	v_fma_f32 v144, -v144, v147, v146
	v_div_fmas_f32 v144, v144, v145, v147
	v_div_fixup_f32 v91, v144, v91, 1.0
	v_div_scale_f32 v144, s[20:21], v92, v92, 1.0
	v_rcp_f32_e32 v145, v144
	v_div_scale_f32 v146, vcc, 1.0, v92, 1.0
	v_fma_f32 v147, -v144, v145, 1.0
	v_fmac_f32_e32 v145, v147, v145
	v_mul_f32_e32 v147, v146, v145
	v_fma_f32 v148, -v144, v147, v146
	v_fmac_f32_e32 v147, v148, v145
	v_fma_f32 v144, -v144, v147, v146
	v_div_fmas_f32 v144, v144, v145, v147
	v_div_fixup_f32 v92, v144, v92, 1.0
	v_div_scale_f32 v144, s[20:21], v93, v93, 1.0
	v_rcp_f32_e32 v145, v144
	v_div_scale_f32 v146, vcc, 1.0, v93, 1.0
	v_fma_f32 v147, -v144, v145, 1.0
	v_fmac_f32_e32 v145, v147, v145
	v_mul_f32_e32 v147, v146, v145
	v_fma_f32 v148, -v144, v147, v146
	v_fmac_f32_e32 v147, v148, v145
	v_fma_f32 v144, -v144, v147, v146
	v_div_fmas_f32 v144, v144, v145, v147
	v_div_fixup_f32 v93, v144, v93, 1.0
	v_cvt_pk_bf16_f32 v94, v94, v95
	v_cvt_pk_bf16_f32 v95, v96, v97
	v_cvt_pk_bf16_f32 v96, v90, v91
	v_cvt_pk_bf16_f32 v97, v92, v93
	v_add_u32_e32 v157, 0xa0000, v156
	global_store_dwordx4 v157, v[94:97], s[44:45]
	v_pk_add_f32 v[86:87], v[86:87], v[10:11]
	v_pk_add_f32 v[88:89], v[88:89], v[12:13]
	v_pk_add_f32 v[82:83], v[82:83], v[14:15]
	v_pk_add_f32 v[84:85], v[84:85], v[16:17]
	v_mul_f32_e32 v86, 0xbfb8aa3b, v86
	v_mul_f32_e32 v87, 0xbfb8aa3b, v87
	v_mul_f32_e32 v88, 0xbfb8aa3b, v88
	v_mul_f32_e32 v89, 0xbfb8aa3b, v89
	v_mul_f32_e32 v82, 0xbfb8aa3b, v82
	v_mul_f32_e32 v83, 0xbfb8aa3b, v83
	v_mul_f32_e32 v84, 0xbfb8aa3b, v84
	v_mul_f32_e32 v85, 0xbfb8aa3b, v85
	v_exp_f32_e32 v86, v86
	v_exp_f32_e32 v87, v87
	v_exp_f32_e32 v88, v88
	v_exp_f32_e32 v89, v89
	v_exp_f32_e32 v82, v82
	v_exp_f32_e32 v83, v83
	v_exp_f32_e32 v84, v84
	v_exp_f32_e32 v85, v85
	v_add_f32_e32 v86, 1.0, v86
	v_add_f32_e32 v87, 1.0, v87
	v_add_f32_e32 v88, 1.0, v88
	v_add_f32_e32 v89, 1.0, v89
	v_add_f32_e32 v82, 1.0, v82
	v_add_f32_e32 v83, 1.0, v83
	v_add_f32_e32 v84, 1.0, v84
	v_add_f32_e32 v85, 1.0, v85
	v_div_scale_f32 v144, s[20:21], v86, v86, 1.0
	v_rcp_f32_e32 v145, v144
	v_div_scale_f32 v146, vcc, 1.0, v86, 1.0
	v_fma_f32 v147, -v144, v145, 1.0
	v_fmac_f32_e32 v145, v147, v145
	v_mul_f32_e32 v147, v146, v145
	v_fma_f32 v148, -v144, v147, v146
	v_fmac_f32_e32 v147, v148, v145
	v_fma_f32 v144, -v144, v147, v146
	v_div_fmas_f32 v144, v144, v145, v147
	v_div_fixup_f32 v86, v144, v86, 1.0
	v_div_scale_f32 v144, s[20:21], v87, v87, 1.0
	v_rcp_f32_e32 v145, v144
	v_div_scale_f32 v146, vcc, 1.0, v87, 1.0
	v_fma_f32 v147, -v144, v145, 1.0
	v_fmac_f32_e32 v145, v147, v145
	v_mul_f32_e32 v147, v146, v145
	v_fma_f32 v148, -v144, v147, v146
	v_fmac_f32_e32 v147, v148, v145
	v_fma_f32 v144, -v144, v147, v146
	v_div_fmas_f32 v144, v144, v145, v147
	v_div_fixup_f32 v87, v144, v87, 1.0
	v_div_scale_f32 v144, s[20:21], v88, v88, 1.0
	v_rcp_f32_e32 v145, v144
	v_div_scale_f32 v146, vcc, 1.0, v88, 1.0
	v_fma_f32 v147, -v144, v145, 1.0
	v_fmac_f32_e32 v145, v147, v145
	v_mul_f32_e32 v147, v146, v145
	v_fma_f32 v148, -v144, v147, v146
	v_fmac_f32_e32 v147, v148, v145
	v_fma_f32 v144, -v144, v147, v146
	v_div_fmas_f32 v144, v144, v145, v147
	v_div_fixup_f32 v88, v144, v88, 1.0
	v_div_scale_f32 v144, s[20:21], v89, v89, 1.0
	v_rcp_f32_e32 v145, v144
	v_div_scale_f32 v146, vcc, 1.0, v89, 1.0
	v_fma_f32 v147, -v144, v145, 1.0
	v_fmac_f32_e32 v145, v147, v145
	v_mul_f32_e32 v147, v146, v145
	v_fma_f32 v148, -v144, v147, v146
	v_fmac_f32_e32 v147, v148, v145
	v_fma_f32 v144, -v144, v147, v146
	v_div_fmas_f32 v144, v144, v145, v147
	v_div_fixup_f32 v89, v144, v89, 1.0
	v_div_scale_f32 v144, s[20:21], v82, v82, 1.0
	v_rcp_f32_e32 v145, v144
	v_div_scale_f32 v146, vcc, 1.0, v82, 1.0
	v_fma_f32 v147, -v144, v145, 1.0
	v_fmac_f32_e32 v145, v147, v145
	v_mul_f32_e32 v147, v146, v145
	v_fma_f32 v148, -v144, v147, v146
	v_fmac_f32_e32 v147, v148, v145
	v_fma_f32 v144, -v144, v147, v146
	v_div_fmas_f32 v144, v144, v145, v147
	v_div_fixup_f32 v82, v144, v82, 1.0
	v_div_scale_f32 v144, s[20:21], v83, v83, 1.0
	v_rcp_f32_e32 v145, v144
	v_div_scale_f32 v146, vcc, 1.0, v83, 1.0
	v_fma_f32 v147, -v144, v145, 1.0
	v_fmac_f32_e32 v145, v147, v145
	v_mul_f32_e32 v147, v146, v145
	v_fma_f32 v148, -v144, v147, v146
	v_fmac_f32_e32 v147, v148, v145
	v_fma_f32 v144, -v144, v147, v146
	v_div_fmas_f32 v144, v144, v145, v147
	v_div_fixup_f32 v83, v144, v83, 1.0
	v_div_scale_f32 v144, s[20:21], v84, v84, 1.0
	v_rcp_f32_e32 v145, v144
	v_div_scale_f32 v146, vcc, 1.0, v84, 1.0
	v_fma_f32 v147, -v144, v145, 1.0
	v_fmac_f32_e32 v145, v147, v145
	v_mul_f32_e32 v147, v146, v145
	v_fma_f32 v148, -v144, v147, v146
	v_fmac_f32_e32 v147, v148, v145
	v_fma_f32 v144, -v144, v147, v146
	v_div_fmas_f32 v144, v144, v145, v147
	v_div_fixup_f32 v84, v144, v84, 1.0
	v_div_scale_f32 v144, s[20:21], v85, v85, 1.0
	v_rcp_f32_e32 v145, v144
	v_div_scale_f32 v146, vcc, 1.0, v85, 1.0
	v_fma_f32 v147, -v144, v145, 1.0
	v_fmac_f32_e32 v145, v147, v145
	v_mul_f32_e32 v147, v146, v145
	v_fma_f32 v148, -v144, v147, v146
	v_fmac_f32_e32 v147, v148, v145
	v_fma_f32 v144, -v144, v147, v146
	v_div_fmas_f32 v144, v144, v145, v147
	v_div_fixup_f32 v85, v144, v85, 1.0
	v_cvt_pk_bf16_f32 v86, v86, v87
	v_cvt_pk_bf16_f32 v87, v88, v89
	v_cvt_pk_bf16_f32 v88, v82, v83
	v_cvt_pk_bf16_f32 v89, v84, v85
	v_add_u32_e32 v157, 0xb0000, v156
	global_store_dwordx4 v157, v[86:89], s[44:45]
	global_load_dwordx4 v[10:13], v153, s[62:63] offset:512
	global_load_dwordx4 v[14:17], v153, s[62:63] offset:528
	s_waitcnt vmcnt(0)
	v_pk_add_f32 v[78:79], v[78:79], v[10:11]
	v_pk_add_f32 v[80:81], v[80:81], v[12:13]
	v_pk_add_f32 v[74:75], v[74:75], v[14:15]
	v_pk_add_f32 v[76:77], v[76:77], v[16:17]
	v_mul_f32_e32 v78, 0xbfb8aa3b, v78
	v_mul_f32_e32 v79, 0xbfb8aa3b, v79
	v_mul_f32_e32 v80, 0xbfb8aa3b, v80
	v_mul_f32_e32 v81, 0xbfb8aa3b, v81
	v_mul_f32_e32 v74, 0xbfb8aa3b, v74
	v_mul_f32_e32 v75, 0xbfb8aa3b, v75
	v_mul_f32_e32 v76, 0xbfb8aa3b, v76
	v_mul_f32_e32 v77, 0xbfb8aa3b, v77
	v_exp_f32_e32 v78, v78
	v_exp_f32_e32 v79, v79
	v_exp_f32_e32 v80, v80
	v_exp_f32_e32 v81, v81
	v_exp_f32_e32 v74, v74
	v_exp_f32_e32 v75, v75
	v_exp_f32_e32 v76, v76
	v_exp_f32_e32 v77, v77
	v_add_f32_e32 v78, 1.0, v78
	v_add_f32_e32 v79, 1.0, v79
	v_add_f32_e32 v80, 1.0, v80
	v_add_f32_e32 v81, 1.0, v81
	v_add_f32_e32 v74, 1.0, v74
	v_add_f32_e32 v75, 1.0, v75
	v_add_f32_e32 v76, 1.0, v76
	v_add_f32_e32 v77, 1.0, v77
	v_div_scale_f32 v144, s[20:21], v78, v78, 1.0
	v_rcp_f32_e32 v145, v144
	v_div_scale_f32 v146, vcc, 1.0, v78, 1.0
	v_fma_f32 v147, -v144, v145, 1.0
	v_fmac_f32_e32 v145, v147, v145
	v_mul_f32_e32 v147, v146, v145
	v_fma_f32 v148, -v144, v147, v146
	v_fmac_f32_e32 v147, v148, v145
	v_fma_f32 v144, -v144, v147, v146
	v_div_fmas_f32 v144, v144, v145, v147
	v_div_fixup_f32 v78, v144, v78, 1.0
	v_div_scale_f32 v144, s[20:21], v79, v79, 1.0
	v_rcp_f32_e32 v145, v144
	v_div_scale_f32 v146, vcc, 1.0, v79, 1.0
	v_fma_f32 v147, -v144, v145, 1.0
	v_fmac_f32_e32 v145, v147, v145
	v_mul_f32_e32 v147, v146, v145
	v_fma_f32 v148, -v144, v147, v146
	v_fmac_f32_e32 v147, v148, v145
	v_fma_f32 v144, -v144, v147, v146
	v_div_fmas_f32 v144, v144, v145, v147
	v_div_fixup_f32 v79, v144, v79, 1.0
	v_div_scale_f32 v144, s[20:21], v80, v80, 1.0
	v_rcp_f32_e32 v145, v144
	v_div_scale_f32 v146, vcc, 1.0, v80, 1.0
	v_fma_f32 v147, -v144, v145, 1.0
	v_fmac_f32_e32 v145, v147, v145
	v_mul_f32_e32 v147, v146, v145
	v_fma_f32 v148, -v144, v147, v146
	v_fmac_f32_e32 v147, v148, v145
	v_fma_f32 v144, -v144, v147, v146
	v_div_fmas_f32 v144, v144, v145, v147
	v_div_fixup_f32 v80, v144, v80, 1.0
	v_div_scale_f32 v144, s[20:21], v81, v81, 1.0
	v_rcp_f32_e32 v145, v144
	v_div_scale_f32 v146, vcc, 1.0, v81, 1.0
	v_fma_f32 v147, -v144, v145, 1.0
	v_fmac_f32_e32 v145, v147, v145
	v_mul_f32_e32 v147, v146, v145
	v_fma_f32 v148, -v144, v147, v146
	v_fmac_f32_e32 v147, v148, v145
	v_fma_f32 v144, -v144, v147, v146
	v_div_fmas_f32 v144, v144, v145, v147
	v_div_fixup_f32 v81, v144, v81, 1.0
	v_div_scale_f32 v144, s[20:21], v74, v74, 1.0
	v_rcp_f32_e32 v145, v144
	v_div_scale_f32 v146, vcc, 1.0, v74, 1.0
	v_fma_f32 v147, -v144, v145, 1.0
	v_fmac_f32_e32 v145, v147, v145
	v_mul_f32_e32 v147, v146, v145
	v_fma_f32 v148, -v144, v147, v146
	v_fmac_f32_e32 v147, v148, v145
	v_fma_f32 v144, -v144, v147, v146
	v_div_fmas_f32 v144, v144, v145, v147
	v_div_fixup_f32 v74, v144, v74, 1.0
	v_div_scale_f32 v144, s[20:21], v75, v75, 1.0
	v_rcp_f32_e32 v145, v144
	v_div_scale_f32 v146, vcc, 1.0, v75, 1.0
	v_fma_f32 v147, -v144, v145, 1.0
	v_fmac_f32_e32 v145, v147, v145
	v_mul_f32_e32 v147, v146, v145
	v_fma_f32 v148, -v144, v147, v146
	v_fmac_f32_e32 v147, v148, v145
	v_fma_f32 v144, -v144, v147, v146
	v_div_fmas_f32 v144, v144, v145, v147
	v_div_fixup_f32 v75, v144, v75, 1.0
	v_div_scale_f32 v144, s[20:21], v76, v76, 1.0
	v_rcp_f32_e32 v145, v144
	v_div_scale_f32 v146, vcc, 1.0, v76, 1.0
	v_fma_f32 v147, -v144, v145, 1.0
	v_fmac_f32_e32 v145, v147, v145
	v_mul_f32_e32 v147, v146, v145
	v_fma_f32 v148, -v144, v147, v146
	v_fmac_f32_e32 v147, v148, v145
	v_fma_f32 v144, -v144, v147, v146
	v_div_fmas_f32 v144, v144, v145, v147
	v_div_fixup_f32 v76, v144, v76, 1.0
	v_div_scale_f32 v144, s[20:21], v77, v77, 1.0
	v_rcp_f32_e32 v145, v144
	v_div_scale_f32 v146, vcc, 1.0, v77, 1.0
	v_fma_f32 v147, -v144, v145, 1.0
	v_fmac_f32_e32 v145, v147, v145
	v_mul_f32_e32 v147, v146, v145
	v_fma_f32 v148, -v144, v147, v146
	v_fmac_f32_e32 v147, v148, v145
	v_fma_f32 v144, -v144, v147, v146
	v_div_fmas_f32 v144, v144, v145, v147
	v_div_fixup_f32 v77, v144, v77, 1.0
	v_cvt_pk_bf16_f32 v78, v78, v79
	v_cvt_pk_bf16_f32 v79, v80, v81
	v_cvt_pk_bf16_f32 v80, v74, v75
	v_cvt_pk_bf16_f32 v81, v76, v77
	global_store_dwordx4 v156, v[78:81], s[44:45] offset:256
	v_pk_add_f32 v[70:71], v[70:71], v[10:11]
	v_pk_add_f32 v[72:73], v[72:73], v[12:13]
	v_pk_add_f32 v[66:67], v[66:67], v[14:15]
	v_pk_add_f32 v[68:69], v[68:69], v[16:17]
	v_mul_f32_e32 v70, 0xbfb8aa3b, v70
	v_mul_f32_e32 v71, 0xbfb8aa3b, v71
	v_mul_f32_e32 v72, 0xbfb8aa3b, v72
	v_mul_f32_e32 v73, 0xbfb8aa3b, v73
	v_mul_f32_e32 v66, 0xbfb8aa3b, v66
	v_mul_f32_e32 v67, 0xbfb8aa3b, v67
	v_mul_f32_e32 v68, 0xbfb8aa3b, v68
	v_mul_f32_e32 v69, 0xbfb8aa3b, v69
	v_exp_f32_e32 v70, v70
	v_exp_f32_e32 v71, v71
	v_exp_f32_e32 v72, v72
	v_exp_f32_e32 v73, v73
	v_exp_f32_e32 v66, v66
	v_exp_f32_e32 v67, v67
	v_exp_f32_e32 v68, v68
	v_exp_f32_e32 v69, v69
	v_add_f32_e32 v70, 1.0, v70
	v_add_f32_e32 v71, 1.0, v71
	v_add_f32_e32 v72, 1.0, v72
	v_add_f32_e32 v73, 1.0, v73
	v_add_f32_e32 v66, 1.0, v66
	v_add_f32_e32 v67, 1.0, v67
	v_add_f32_e32 v68, 1.0, v68
	v_add_f32_e32 v69, 1.0, v69
	v_div_scale_f32 v144, s[20:21], v70, v70, 1.0
	v_rcp_f32_e32 v145, v144
	v_div_scale_f32 v146, vcc, 1.0, v70, 1.0
	v_fma_f32 v147, -v144, v145, 1.0
	v_fmac_f32_e32 v145, v147, v145
	v_mul_f32_e32 v147, v146, v145
	v_fma_f32 v148, -v144, v147, v146
	v_fmac_f32_e32 v147, v148, v145
	v_fma_f32 v144, -v144, v147, v146
	v_div_fmas_f32 v144, v144, v145, v147
	v_div_fixup_f32 v70, v144, v70, 1.0
	v_div_scale_f32 v144, s[20:21], v71, v71, 1.0
	v_rcp_f32_e32 v145, v144
	v_div_scale_f32 v146, vcc, 1.0, v71, 1.0
	v_fma_f32 v147, -v144, v145, 1.0
	v_fmac_f32_e32 v145, v147, v145
	v_mul_f32_e32 v147, v146, v145
	v_fma_f32 v148, -v144, v147, v146
	v_fmac_f32_e32 v147, v148, v145
	v_fma_f32 v144, -v144, v147, v146
	v_div_fmas_f32 v144, v144, v145, v147
	v_div_fixup_f32 v71, v144, v71, 1.0
	v_div_scale_f32 v144, s[20:21], v72, v72, 1.0
	v_rcp_f32_e32 v145, v144
	v_div_scale_f32 v146, vcc, 1.0, v72, 1.0
	v_fma_f32 v147, -v144, v145, 1.0
	v_fmac_f32_e32 v145, v147, v145
	v_mul_f32_e32 v147, v146, v145
	v_fma_f32 v148, -v144, v147, v146
	v_fmac_f32_e32 v147, v148, v145
	v_fma_f32 v144, -v144, v147, v146
	v_div_fmas_f32 v144, v144, v145, v147
	v_div_fixup_f32 v72, v144, v72, 1.0
	v_div_scale_f32 v144, s[20:21], v73, v73, 1.0
	v_rcp_f32_e32 v145, v144
	v_div_scale_f32 v146, vcc, 1.0, v73, 1.0
	v_fma_f32 v147, -v144, v145, 1.0
	v_fmac_f32_e32 v145, v147, v145
	v_mul_f32_e32 v147, v146, v145
	v_fma_f32 v148, -v144, v147, v146
	v_fmac_f32_e32 v147, v148, v145
	v_fma_f32 v144, -v144, v147, v146
	v_div_fmas_f32 v144, v144, v145, v147
	v_div_fixup_f32 v73, v144, v73, 1.0
	v_div_scale_f32 v144, s[20:21], v66, v66, 1.0
	v_rcp_f32_e32 v145, v144
	v_div_scale_f32 v146, vcc, 1.0, v66, 1.0
	v_fma_f32 v147, -v144, v145, 1.0
	v_fmac_f32_e32 v145, v147, v145
	v_mul_f32_e32 v147, v146, v145
	v_fma_f32 v148, -v144, v147, v146
	v_fmac_f32_e32 v147, v148, v145
	v_fma_f32 v144, -v144, v147, v146
	v_div_fmas_f32 v144, v144, v145, v147
	v_div_fixup_f32 v66, v144, v66, 1.0
	v_div_scale_f32 v144, s[20:21], v67, v67, 1.0
	v_rcp_f32_e32 v145, v144
	v_div_scale_f32 v146, vcc, 1.0, v67, 1.0
	v_fma_f32 v147, -v144, v145, 1.0
	v_fmac_f32_e32 v145, v147, v145
	v_mul_f32_e32 v147, v146, v145
	v_fma_f32 v148, -v144, v147, v146
	v_fmac_f32_e32 v147, v148, v145
	v_fma_f32 v144, -v144, v147, v146
	v_div_fmas_f32 v144, v144, v145, v147
	v_div_fixup_f32 v67, v144, v67, 1.0
	v_div_scale_f32 v144, s[20:21], v68, v68, 1.0
	v_rcp_f32_e32 v145, v144
	v_div_scale_f32 v146, vcc, 1.0, v68, 1.0
	v_fma_f32 v147, -v144, v145, 1.0
	v_fmac_f32_e32 v145, v147, v145
	v_mul_f32_e32 v147, v146, v145
	v_fma_f32 v148, -v144, v147, v146
	v_fmac_f32_e32 v147, v148, v145
	v_fma_f32 v144, -v144, v147, v146
	v_div_fmas_f32 v144, v144, v145, v147
	v_div_fixup_f32 v68, v144, v68, 1.0
	v_div_scale_f32 v144, s[20:21], v69, v69, 1.0
	v_rcp_f32_e32 v145, v144
	v_div_scale_f32 v146, vcc, 1.0, v69, 1.0
	v_fma_f32 v147, -v144, v145, 1.0
	v_fmac_f32_e32 v145, v147, v145
	v_mul_f32_e32 v147, v146, v145
	v_fma_f32 v148, -v144, v147, v146
	v_fmac_f32_e32 v147, v148, v145
	v_fma_f32 v144, -v144, v147, v146
	v_div_fmas_f32 v144, v144, v145, v147
	v_div_fixup_f32 v69, v144, v69, 1.0
	v_cvt_pk_bf16_f32 v70, v70, v71
	v_cvt_pk_bf16_f32 v71, v72, v73
	v_cvt_pk_bf16_f32 v72, v66, v67
	v_cvt_pk_bf16_f32 v73, v68, v69
	v_add_u32_e32 v157, 0x10000, v156
	global_store_dwordx4 v157, v[70:73], s[44:45] offset:256
	v_pk_add_f32 v[62:63], v[62:63], v[10:11]
	v_pk_add_f32 v[64:65], v[64:65], v[12:13]
	v_pk_add_f32 v[58:59], v[58:59], v[14:15]
	v_pk_add_f32 v[60:61], v[60:61], v[16:17]
	v_mul_f32_e32 v62, 0xbfb8aa3b, v62
	v_mul_f32_e32 v63, 0xbfb8aa3b, v63
	v_mul_f32_e32 v64, 0xbfb8aa3b, v64
	v_mul_f32_e32 v65, 0xbfb8aa3b, v65
	v_mul_f32_e32 v58, 0xbfb8aa3b, v58
	v_mul_f32_e32 v59, 0xbfb8aa3b, v59
	v_mul_f32_e32 v60, 0xbfb8aa3b, v60
	v_mul_f32_e32 v61, 0xbfb8aa3b, v61
	v_exp_f32_e32 v62, v62
	v_exp_f32_e32 v63, v63
	v_exp_f32_e32 v64, v64
	v_exp_f32_e32 v65, v65
	v_exp_f32_e32 v58, v58
	v_exp_f32_e32 v59, v59
	v_exp_f32_e32 v60, v60
	v_exp_f32_e32 v61, v61
	v_add_f32_e32 v62, 1.0, v62
	v_add_f32_e32 v63, 1.0, v63
	v_add_f32_e32 v64, 1.0, v64
	v_add_f32_e32 v65, 1.0, v65
	v_add_f32_e32 v58, 1.0, v58
	v_add_f32_e32 v59, 1.0, v59
	v_add_f32_e32 v60, 1.0, v60
	v_add_f32_e32 v61, 1.0, v61
	v_div_scale_f32 v144, s[20:21], v62, v62, 1.0
	v_rcp_f32_e32 v145, v144
	v_div_scale_f32 v146, vcc, 1.0, v62, 1.0
	v_fma_f32 v147, -v144, v145, 1.0
	v_fmac_f32_e32 v145, v147, v145
	v_mul_f32_e32 v147, v146, v145
	v_fma_f32 v148, -v144, v147, v146
	v_fmac_f32_e32 v147, v148, v145
	v_fma_f32 v144, -v144, v147, v146
	v_div_fmas_f32 v144, v144, v145, v147
	v_div_fixup_f32 v62, v144, v62, 1.0
	v_div_scale_f32 v144, s[20:21], v63, v63, 1.0
	v_rcp_f32_e32 v145, v144
	v_div_scale_f32 v146, vcc, 1.0, v63, 1.0
	v_fma_f32 v147, -v144, v145, 1.0
	v_fmac_f32_e32 v145, v147, v145
	v_mul_f32_e32 v147, v146, v145
	v_fma_f32 v148, -v144, v147, v146
	v_fmac_f32_e32 v147, v148, v145
	v_fma_f32 v144, -v144, v147, v146
	v_div_fmas_f32 v144, v144, v145, v147
	v_div_fixup_f32 v63, v144, v63, 1.0
	v_div_scale_f32 v144, s[20:21], v64, v64, 1.0
	v_rcp_f32_e32 v145, v144
	v_div_scale_f32 v146, vcc, 1.0, v64, 1.0
	v_fma_f32 v147, -v144, v145, 1.0
	v_fmac_f32_e32 v145, v147, v145
	v_mul_f32_e32 v147, v146, v145
	v_fma_f32 v148, -v144, v147, v146
	v_fmac_f32_e32 v147, v148, v145
	v_fma_f32 v144, -v144, v147, v146
	v_div_fmas_f32 v144, v144, v145, v147
	v_div_fixup_f32 v64, v144, v64, 1.0
	v_div_scale_f32 v144, s[20:21], v65, v65, 1.0
	v_rcp_f32_e32 v145, v144
	v_div_scale_f32 v146, vcc, 1.0, v65, 1.0
	v_fma_f32 v147, -v144, v145, 1.0
	v_fmac_f32_e32 v145, v147, v145
	v_mul_f32_e32 v147, v146, v145
	v_fma_f32 v148, -v144, v147, v146
	v_fmac_f32_e32 v147, v148, v145
	v_fma_f32 v144, -v144, v147, v146
	v_div_fmas_f32 v144, v144, v145, v147
	v_div_fixup_f32 v65, v144, v65, 1.0
	v_div_scale_f32 v144, s[20:21], v58, v58, 1.0
	v_rcp_f32_e32 v145, v144
	v_div_scale_f32 v146, vcc, 1.0, v58, 1.0
	v_fma_f32 v147, -v144, v145, 1.0
	v_fmac_f32_e32 v145, v147, v145
	v_mul_f32_e32 v147, v146, v145
	v_fma_f32 v148, -v144, v147, v146
	v_fmac_f32_e32 v147, v148, v145
	v_fma_f32 v144, -v144, v147, v146
	v_div_fmas_f32 v144, v144, v145, v147
	v_div_fixup_f32 v58, v144, v58, 1.0
	v_div_scale_f32 v144, s[20:21], v59, v59, 1.0
	v_rcp_f32_e32 v145, v144
	v_div_scale_f32 v146, vcc, 1.0, v59, 1.0
	v_fma_f32 v147, -v144, v145, 1.0
	v_fmac_f32_e32 v145, v147, v145
	v_mul_f32_e32 v147, v146, v145
	v_fma_f32 v148, -v144, v147, v146
	v_fmac_f32_e32 v147, v148, v145
	v_fma_f32 v144, -v144, v147, v146
	v_div_fmas_f32 v144, v144, v145, v147
	v_div_fixup_f32 v59, v144, v59, 1.0
	v_div_scale_f32 v144, s[20:21], v60, v60, 1.0
	v_rcp_f32_e32 v145, v144
	v_div_scale_f32 v146, vcc, 1.0, v60, 1.0
	v_fma_f32 v147, -v144, v145, 1.0
	v_fmac_f32_e32 v145, v147, v145
	v_mul_f32_e32 v147, v146, v145
	v_fma_f32 v148, -v144, v147, v146
	v_fmac_f32_e32 v147, v148, v145
	v_fma_f32 v144, -v144, v147, v146
	v_div_fmas_f32 v144, v144, v145, v147
	v_div_fixup_f32 v60, v144, v60, 1.0
	v_div_scale_f32 v144, s[20:21], v61, v61, 1.0
	v_rcp_f32_e32 v145, v144
	v_div_scale_f32 v146, vcc, 1.0, v61, 1.0
	v_fma_f32 v147, -v144, v145, 1.0
	v_fmac_f32_e32 v145, v147, v145
	v_mul_f32_e32 v147, v146, v145
	v_fma_f32 v148, -v144, v147, v146
	v_fmac_f32_e32 v147, v148, v145
	v_fma_f32 v144, -v144, v147, v146
	v_div_fmas_f32 v144, v144, v145, v147
	v_div_fixup_f32 v61, v144, v61, 1.0
	v_cvt_pk_bf16_f32 v62, v62, v63
	v_cvt_pk_bf16_f32 v63, v64, v65
	v_cvt_pk_bf16_f32 v64, v58, v59
	v_cvt_pk_bf16_f32 v65, v60, v61
	v_add_u32_e32 v157, 0x20000, v156
	global_store_dwordx4 v157, v[62:65], s[44:45] offset:256
	v_pk_add_f32 v[54:55], v[54:55], v[10:11]
	v_pk_add_f32 v[56:57], v[56:57], v[12:13]
	v_pk_add_f32 v[50:51], v[50:51], v[14:15]
	v_pk_add_f32 v[52:53], v[52:53], v[16:17]
	v_mul_f32_e32 v54, 0xbfb8aa3b, v54
	v_mul_f32_e32 v55, 0xbfb8aa3b, v55
	v_mul_f32_e32 v56, 0xbfb8aa3b, v56
	v_mul_f32_e32 v57, 0xbfb8aa3b, v57
	v_mul_f32_e32 v50, 0xbfb8aa3b, v50
	v_mul_f32_e32 v51, 0xbfb8aa3b, v51
	v_mul_f32_e32 v52, 0xbfb8aa3b, v52
	v_mul_f32_e32 v53, 0xbfb8aa3b, v53
	v_exp_f32_e32 v54, v54
	v_exp_f32_e32 v55, v55
	v_exp_f32_e32 v56, v56
	v_exp_f32_e32 v57, v57
	v_exp_f32_e32 v50, v50
	v_exp_f32_e32 v51, v51
	v_exp_f32_e32 v52, v52
	v_exp_f32_e32 v53, v53
	v_add_f32_e32 v54, 1.0, v54
	v_add_f32_e32 v55, 1.0, v55
	v_add_f32_e32 v56, 1.0, v56
	v_add_f32_e32 v57, 1.0, v57
	v_add_f32_e32 v50, 1.0, v50
	v_add_f32_e32 v51, 1.0, v51
	v_add_f32_e32 v52, 1.0, v52
	v_add_f32_e32 v53, 1.0, v53
	v_div_scale_f32 v144, s[20:21], v54, v54, 1.0
	v_rcp_f32_e32 v145, v144
	v_div_scale_f32 v146, vcc, 1.0, v54, 1.0
	v_fma_f32 v147, -v144, v145, 1.0
	v_fmac_f32_e32 v145, v147, v145
	v_mul_f32_e32 v147, v146, v145
	v_fma_f32 v148, -v144, v147, v146
	v_fmac_f32_e32 v147, v148, v145
	v_fma_f32 v144, -v144, v147, v146
	v_div_fmas_f32 v144, v144, v145, v147
	v_div_fixup_f32 v54, v144, v54, 1.0
	v_div_scale_f32 v144, s[20:21], v55, v55, 1.0
	v_rcp_f32_e32 v145, v144
	v_div_scale_f32 v146, vcc, 1.0, v55, 1.0
	v_fma_f32 v147, -v144, v145, 1.0
	v_fmac_f32_e32 v145, v147, v145
	v_mul_f32_e32 v147, v146, v145
	v_fma_f32 v148, -v144, v147, v146
	v_fmac_f32_e32 v147, v148, v145
	v_fma_f32 v144, -v144, v147, v146
	v_div_fmas_f32 v144, v144, v145, v147
	v_div_fixup_f32 v55, v144, v55, 1.0
	v_div_scale_f32 v144, s[20:21], v56, v56, 1.0
	v_rcp_f32_e32 v145, v144
	v_div_scale_f32 v146, vcc, 1.0, v56, 1.0
	v_fma_f32 v147, -v144, v145, 1.0
	v_fmac_f32_e32 v145, v147, v145
	v_mul_f32_e32 v147, v146, v145
	v_fma_f32 v148, -v144, v147, v146
	v_fmac_f32_e32 v147, v148, v145
	v_fma_f32 v144, -v144, v147, v146
	v_div_fmas_f32 v144, v144, v145, v147
	v_div_fixup_f32 v56, v144, v56, 1.0
	v_div_scale_f32 v144, s[20:21], v57, v57, 1.0
	v_rcp_f32_e32 v145, v144
	v_div_scale_f32 v146, vcc, 1.0, v57, 1.0
	v_fma_f32 v147, -v144, v145, 1.0
	v_fmac_f32_e32 v145, v147, v145
	v_mul_f32_e32 v147, v146, v145
	v_fma_f32 v148, -v144, v147, v146
	v_fmac_f32_e32 v147, v148, v145
	v_fma_f32 v144, -v144, v147, v146
	v_div_fmas_f32 v144, v144, v145, v147
	v_div_fixup_f32 v57, v144, v57, 1.0
	v_div_scale_f32 v144, s[20:21], v50, v50, 1.0
	v_rcp_f32_e32 v145, v144
	v_div_scale_f32 v146, vcc, 1.0, v50, 1.0
	v_fma_f32 v147, -v144, v145, 1.0
	v_fmac_f32_e32 v145, v147, v145
	v_mul_f32_e32 v147, v146, v145
	v_fma_f32 v148, -v144, v147, v146
	v_fmac_f32_e32 v147, v148, v145
	v_fma_f32 v144, -v144, v147, v146
	v_div_fmas_f32 v144, v144, v145, v147
	v_div_fixup_f32 v50, v144, v50, 1.0
	v_div_scale_f32 v144, s[20:21], v51, v51, 1.0
	v_rcp_f32_e32 v145, v144
	v_div_scale_f32 v146, vcc, 1.0, v51, 1.0
	v_fma_f32 v147, -v144, v145, 1.0
	v_fmac_f32_e32 v145, v147, v145
	v_mul_f32_e32 v147, v146, v145
	v_fma_f32 v148, -v144, v147, v146
	v_fmac_f32_e32 v147, v148, v145
	v_fma_f32 v144, -v144, v147, v146
	v_div_fmas_f32 v144, v144, v145, v147
	v_div_fixup_f32 v51, v144, v51, 1.0
	v_div_scale_f32 v144, s[20:21], v52, v52, 1.0
	v_rcp_f32_e32 v145, v144
	v_div_scale_f32 v146, vcc, 1.0, v52, 1.0
	v_fma_f32 v147, -v144, v145, 1.0
	v_fmac_f32_e32 v145, v147, v145
	v_mul_f32_e32 v147, v146, v145
	v_fma_f32 v148, -v144, v147, v146
	v_fmac_f32_e32 v147, v148, v145
	v_fma_f32 v144, -v144, v147, v146
	v_div_fmas_f32 v144, v144, v145, v147
	v_div_fixup_f32 v52, v144, v52, 1.0
	v_div_scale_f32 v144, s[20:21], v53, v53, 1.0
	v_rcp_f32_e32 v145, v144
	v_div_scale_f32 v146, vcc, 1.0, v53, 1.0
	v_fma_f32 v147, -v144, v145, 1.0
	v_fmac_f32_e32 v145, v147, v145
	v_mul_f32_e32 v147, v146, v145
	v_fma_f32 v148, -v144, v147, v146
	v_fmac_f32_e32 v147, v148, v145
	v_fma_f32 v144, -v144, v147, v146
	v_div_fmas_f32 v144, v144, v145, v147
	v_div_fixup_f32 v53, v144, v53, 1.0
	v_cvt_pk_bf16_f32 v54, v54, v55
	v_cvt_pk_bf16_f32 v55, v56, v57
	v_cvt_pk_bf16_f32 v56, v50, v51
	v_cvt_pk_bf16_f32 v57, v52, v53
	v_add_u32_e32 v157, 0x30000, v156
	global_store_dwordx4 v157, v[54:57], s[44:45] offset:256
	v_pk_add_f32 v[46:47], v[46:47], v[10:11]
	v_pk_add_f32 v[48:49], v[48:49], v[12:13]
	v_pk_add_f32 v[42:43], v[42:43], v[14:15]
	v_pk_add_f32 v[44:45], v[44:45], v[16:17]
	v_mul_f32_e32 v46, 0xbfb8aa3b, v46
	v_mul_f32_e32 v47, 0xbfb8aa3b, v47
	v_mul_f32_e32 v48, 0xbfb8aa3b, v48
	v_mul_f32_e32 v49, 0xbfb8aa3b, v49
	v_mul_f32_e32 v42, 0xbfb8aa3b, v42
	v_mul_f32_e32 v43, 0xbfb8aa3b, v43
	v_mul_f32_e32 v44, 0xbfb8aa3b, v44
	v_mul_f32_e32 v45, 0xbfb8aa3b, v45
	v_exp_f32_e32 v46, v46
	v_exp_f32_e32 v47, v47
	v_exp_f32_e32 v48, v48
	v_exp_f32_e32 v49, v49
	v_exp_f32_e32 v42, v42
	v_exp_f32_e32 v43, v43
	v_exp_f32_e32 v44, v44
	v_exp_f32_e32 v45, v45
	v_add_f32_e32 v46, 1.0, v46
	v_add_f32_e32 v47, 1.0, v47
	v_add_f32_e32 v48, 1.0, v48
	v_add_f32_e32 v49, 1.0, v49
	v_add_f32_e32 v42, 1.0, v42
	v_add_f32_e32 v43, 1.0, v43
	v_add_f32_e32 v44, 1.0, v44
	v_add_f32_e32 v45, 1.0, v45
	v_div_scale_f32 v144, s[20:21], v46, v46, 1.0
	v_rcp_f32_e32 v145, v144
	v_div_scale_f32 v146, vcc, 1.0, v46, 1.0
	v_fma_f32 v147, -v144, v145, 1.0
	v_fmac_f32_e32 v145, v147, v145
	v_mul_f32_e32 v147, v146, v145
	v_fma_f32 v148, -v144, v147, v146
	v_fmac_f32_e32 v147, v148, v145
	v_fma_f32 v144, -v144, v147, v146
	v_div_fmas_f32 v144, v144, v145, v147
	v_div_fixup_f32 v46, v144, v46, 1.0
	v_div_scale_f32 v144, s[20:21], v47, v47, 1.0
	v_rcp_f32_e32 v145, v144
	v_div_scale_f32 v146, vcc, 1.0, v47, 1.0
	v_fma_f32 v147, -v144, v145, 1.0
	v_fmac_f32_e32 v145, v147, v145
	v_mul_f32_e32 v147, v146, v145
	v_fma_f32 v148, -v144, v147, v146
	v_fmac_f32_e32 v147, v148, v145
	v_fma_f32 v144, -v144, v147, v146
	v_div_fmas_f32 v144, v144, v145, v147
	v_div_fixup_f32 v47, v144, v47, 1.0
	v_div_scale_f32 v144, s[20:21], v48, v48, 1.0
	v_rcp_f32_e32 v145, v144
	v_div_scale_f32 v146, vcc, 1.0, v48, 1.0
	v_fma_f32 v147, -v144, v145, 1.0
	v_fmac_f32_e32 v145, v147, v145
	v_mul_f32_e32 v147, v146, v145
	v_fma_f32 v148, -v144, v147, v146
	v_fmac_f32_e32 v147, v148, v145
	v_fma_f32 v144, -v144, v147, v146
	v_div_fmas_f32 v144, v144, v145, v147
	v_div_fixup_f32 v48, v144, v48, 1.0
	v_div_scale_f32 v144, s[20:21], v49, v49, 1.0
	v_rcp_f32_e32 v145, v144
	v_div_scale_f32 v146, vcc, 1.0, v49, 1.0
	v_fma_f32 v147, -v144, v145, 1.0
	v_fmac_f32_e32 v145, v147, v145
	v_mul_f32_e32 v147, v146, v145
	v_fma_f32 v148, -v144, v147, v146
	v_fmac_f32_e32 v147, v148, v145
	v_fma_f32 v144, -v144, v147, v146
	v_div_fmas_f32 v144, v144, v145, v147
	v_div_fixup_f32 v49, v144, v49, 1.0
	v_div_scale_f32 v144, s[20:21], v42, v42, 1.0
	v_rcp_f32_e32 v145, v144
	v_div_scale_f32 v146, vcc, 1.0, v42, 1.0
	v_fma_f32 v147, -v144, v145, 1.0
	v_fmac_f32_e32 v145, v147, v145
	v_mul_f32_e32 v147, v146, v145
	v_fma_f32 v148, -v144, v147, v146
	v_fmac_f32_e32 v147, v148, v145
	v_fma_f32 v144, -v144, v147, v146
	v_div_fmas_f32 v144, v144, v145, v147
	v_div_fixup_f32 v42, v144, v42, 1.0
	v_div_scale_f32 v144, s[20:21], v43, v43, 1.0
	v_rcp_f32_e32 v145, v144
	v_div_scale_f32 v146, vcc, 1.0, v43, 1.0
	v_fma_f32 v147, -v144, v145, 1.0
	v_fmac_f32_e32 v145, v147, v145
	v_mul_f32_e32 v147, v146, v145
	v_fma_f32 v148, -v144, v147, v146
	v_fmac_f32_e32 v147, v148, v145
	v_fma_f32 v144, -v144, v147, v146
	v_div_fmas_f32 v144, v144, v145, v147
	v_div_fixup_f32 v43, v144, v43, 1.0
	v_div_scale_f32 v144, s[20:21], v44, v44, 1.0
	v_rcp_f32_e32 v145, v144
	v_div_scale_f32 v146, vcc, 1.0, v44, 1.0
	v_fma_f32 v147, -v144, v145, 1.0
	v_fmac_f32_e32 v145, v147, v145
	v_mul_f32_e32 v147, v146, v145
	v_fma_f32 v148, -v144, v147, v146
	v_fmac_f32_e32 v147, v148, v145
	v_fma_f32 v144, -v144, v147, v146
	v_div_fmas_f32 v144, v144, v145, v147
	v_div_fixup_f32 v44, v144, v44, 1.0
	v_div_scale_f32 v144, s[20:21], v45, v45, 1.0
	v_rcp_f32_e32 v145, v144
	v_div_scale_f32 v146, vcc, 1.0, v45, 1.0
	v_fma_f32 v147, -v144, v145, 1.0
	v_fmac_f32_e32 v145, v147, v145
	v_mul_f32_e32 v147, v146, v145
	v_fma_f32 v148, -v144, v147, v146
	v_fmac_f32_e32 v147, v148, v145
	v_fma_f32 v144, -v144, v147, v146
	v_div_fmas_f32 v144, v144, v145, v147
	v_div_fixup_f32 v45, v144, v45, 1.0
	v_cvt_pk_bf16_f32 v46, v46, v47
	v_cvt_pk_bf16_f32 v47, v48, v49
	v_cvt_pk_bf16_f32 v48, v42, v43
	v_cvt_pk_bf16_f32 v49, v44, v45
	v_add_u32_e32 v157, 0x80000, v156
	global_store_dwordx4 v157, v[46:49], s[44:45] offset:256
	v_pk_add_f32 v[38:39], v[38:39], v[10:11]
	v_pk_add_f32 v[40:41], v[40:41], v[12:13]
	v_pk_add_f32 v[34:35], v[34:35], v[14:15]
	v_pk_add_f32 v[36:37], v[36:37], v[16:17]
	v_mul_f32_e32 v38, 0xbfb8aa3b, v38
	v_mul_f32_e32 v39, 0xbfb8aa3b, v39
	v_mul_f32_e32 v40, 0xbfb8aa3b, v40
	v_mul_f32_e32 v41, 0xbfb8aa3b, v41
	v_mul_f32_e32 v34, 0xbfb8aa3b, v34
	v_mul_f32_e32 v35, 0xbfb8aa3b, v35
	v_mul_f32_e32 v36, 0xbfb8aa3b, v36
	v_mul_f32_e32 v37, 0xbfb8aa3b, v37
	v_exp_f32_e32 v38, v38
	v_exp_f32_e32 v39, v39
	v_exp_f32_e32 v40, v40
	v_exp_f32_e32 v41, v41
	v_exp_f32_e32 v34, v34
	v_exp_f32_e32 v35, v35
	v_exp_f32_e32 v36, v36
	v_exp_f32_e32 v37, v37
	v_add_f32_e32 v38, 1.0, v38
	v_add_f32_e32 v39, 1.0, v39
	v_add_f32_e32 v40, 1.0, v40
	v_add_f32_e32 v41, 1.0, v41
	v_add_f32_e32 v34, 1.0, v34
	v_add_f32_e32 v35, 1.0, v35
	v_add_f32_e32 v36, 1.0, v36
	v_add_f32_e32 v37, 1.0, v37
	v_div_scale_f32 v144, s[20:21], v38, v38, 1.0
	v_rcp_f32_e32 v145, v144
	v_div_scale_f32 v146, vcc, 1.0, v38, 1.0
	v_fma_f32 v147, -v144, v145, 1.0
	v_fmac_f32_e32 v145, v147, v145
	v_mul_f32_e32 v147, v146, v145
	v_fma_f32 v148, -v144, v147, v146
	v_fmac_f32_e32 v147, v148, v145
	v_fma_f32 v144, -v144, v147, v146
	v_div_fmas_f32 v144, v144, v145, v147
	v_div_fixup_f32 v38, v144, v38, 1.0
	v_div_scale_f32 v144, s[20:21], v39, v39, 1.0
	v_rcp_f32_e32 v145, v144
	v_div_scale_f32 v146, vcc, 1.0, v39, 1.0
	v_fma_f32 v147, -v144, v145, 1.0
	v_fmac_f32_e32 v145, v147, v145
	v_mul_f32_e32 v147, v146, v145
	v_fma_f32 v148, -v144, v147, v146
	v_fmac_f32_e32 v147, v148, v145
	v_fma_f32 v144, -v144, v147, v146
	v_div_fmas_f32 v144, v144, v145, v147
	v_div_fixup_f32 v39, v144, v39, 1.0
	v_div_scale_f32 v144, s[20:21], v40, v40, 1.0
	v_rcp_f32_e32 v145, v144
	v_div_scale_f32 v146, vcc, 1.0, v40, 1.0
	v_fma_f32 v147, -v144, v145, 1.0
	v_fmac_f32_e32 v145, v147, v145
	v_mul_f32_e32 v147, v146, v145
	v_fma_f32 v148, -v144, v147, v146
	v_fmac_f32_e32 v147, v148, v145
	v_fma_f32 v144, -v144, v147, v146
	v_div_fmas_f32 v144, v144, v145, v147
	v_div_fixup_f32 v40, v144, v40, 1.0
	v_div_scale_f32 v144, s[20:21], v41, v41, 1.0
	v_rcp_f32_e32 v145, v144
	v_div_scale_f32 v146, vcc, 1.0, v41, 1.0
	v_fma_f32 v147, -v144, v145, 1.0
	v_fmac_f32_e32 v145, v147, v145
	v_mul_f32_e32 v147, v146, v145
	v_fma_f32 v148, -v144, v147, v146
	v_fmac_f32_e32 v147, v148, v145
	v_fma_f32 v144, -v144, v147, v146
	v_div_fmas_f32 v144, v144, v145, v147
	v_div_fixup_f32 v41, v144, v41, 1.0
	v_div_scale_f32 v144, s[20:21], v34, v34, 1.0
	v_rcp_f32_e32 v145, v144
	v_div_scale_f32 v146, vcc, 1.0, v34, 1.0
	v_fma_f32 v147, -v144, v145, 1.0
	v_fmac_f32_e32 v145, v147, v145
	v_mul_f32_e32 v147, v146, v145
	v_fma_f32 v148, -v144, v147, v146
	v_fmac_f32_e32 v147, v148, v145
	v_fma_f32 v144, -v144, v147, v146
	v_div_fmas_f32 v144, v144, v145, v147
	v_div_fixup_f32 v34, v144, v34, 1.0
	v_div_scale_f32 v144, s[20:21], v35, v35, 1.0
	v_rcp_f32_e32 v145, v144
	v_div_scale_f32 v146, vcc, 1.0, v35, 1.0
	v_fma_f32 v147, -v144, v145, 1.0
	v_fmac_f32_e32 v145, v147, v145
	v_mul_f32_e32 v147, v146, v145
	v_fma_f32 v148, -v144, v147, v146
	v_fmac_f32_e32 v147, v148, v145
	v_fma_f32 v144, -v144, v147, v146
	v_div_fmas_f32 v144, v144, v145, v147
	v_div_fixup_f32 v35, v144, v35, 1.0
	v_div_scale_f32 v144, s[20:21], v36, v36, 1.0
	v_rcp_f32_e32 v145, v144
	v_div_scale_f32 v146, vcc, 1.0, v36, 1.0
	v_fma_f32 v147, -v144, v145, 1.0
	v_fmac_f32_e32 v145, v147, v145
	v_mul_f32_e32 v147, v146, v145
	v_fma_f32 v148, -v144, v147, v146
	v_fmac_f32_e32 v147, v148, v145
	v_fma_f32 v144, -v144, v147, v146
	v_div_fmas_f32 v144, v144, v145, v147
	v_div_fixup_f32 v36, v144, v36, 1.0
	v_div_scale_f32 v144, s[20:21], v37, v37, 1.0
	v_rcp_f32_e32 v145, v144
	v_div_scale_f32 v146, vcc, 1.0, v37, 1.0
	v_fma_f32 v147, -v144, v145, 1.0
	v_fmac_f32_e32 v145, v147, v145
	v_mul_f32_e32 v147, v146, v145
	v_fma_f32 v148, -v144, v147, v146
	v_fmac_f32_e32 v147, v148, v145
	v_fma_f32 v144, -v144, v147, v146
	v_div_fmas_f32 v144, v144, v145, v147
	v_div_fixup_f32 v37, v144, v37, 1.0
	v_cvt_pk_bf16_f32 v38, v38, v39
	v_cvt_pk_bf16_f32 v39, v40, v41
	v_cvt_pk_bf16_f32 v40, v34, v35
	v_cvt_pk_bf16_f32 v41, v36, v37
	v_add_u32_e32 v157, 0x90000, v156
	global_store_dwordx4 v157, v[38:41], s[44:45] offset:256
	v_pk_add_f32 v[30:31], v[30:31], v[10:11]
	v_pk_add_f32 v[32:33], v[32:33], v[12:13]
	v_pk_add_f32 v[26:27], v[26:27], v[14:15]
	v_pk_add_f32 v[28:29], v[28:29], v[16:17]
	v_mul_f32_e32 v30, 0xbfb8aa3b, v30
	v_mul_f32_e32 v31, 0xbfb8aa3b, v31
	v_mul_f32_e32 v32, 0xbfb8aa3b, v32
	v_mul_f32_e32 v33, 0xbfb8aa3b, v33
	v_mul_f32_e32 v26, 0xbfb8aa3b, v26
	v_mul_f32_e32 v27, 0xbfb8aa3b, v27
	v_mul_f32_e32 v28, 0xbfb8aa3b, v28
	v_mul_f32_e32 v29, 0xbfb8aa3b, v29
	v_exp_f32_e32 v30, v30
	v_exp_f32_e32 v31, v31
	v_exp_f32_e32 v32, v32
	v_exp_f32_e32 v33, v33
	v_exp_f32_e32 v26, v26
	v_exp_f32_e32 v27, v27
	v_exp_f32_e32 v28, v28
	v_exp_f32_e32 v29, v29
	v_add_f32_e32 v30, 1.0, v30
	v_add_f32_e32 v31, 1.0, v31
	v_add_f32_e32 v32, 1.0, v32
	v_add_f32_e32 v33, 1.0, v33
	v_add_f32_e32 v26, 1.0, v26
	v_add_f32_e32 v27, 1.0, v27
	v_add_f32_e32 v28, 1.0, v28
	v_add_f32_e32 v29, 1.0, v29
	v_div_scale_f32 v144, s[20:21], v30, v30, 1.0
	v_rcp_f32_e32 v145, v144
	v_div_scale_f32 v146, vcc, 1.0, v30, 1.0
	v_fma_f32 v147, -v144, v145, 1.0
	v_fmac_f32_e32 v145, v147, v145
	v_mul_f32_e32 v147, v146, v145
	v_fma_f32 v148, -v144, v147, v146
	v_fmac_f32_e32 v147, v148, v145
	v_fma_f32 v144, -v144, v147, v146
	v_div_fmas_f32 v144, v144, v145, v147
	v_div_fixup_f32 v30, v144, v30, 1.0
	v_div_scale_f32 v144, s[20:21], v31, v31, 1.0
	v_rcp_f32_e32 v145, v144
	v_div_scale_f32 v146, vcc, 1.0, v31, 1.0
	v_fma_f32 v147, -v144, v145, 1.0
	v_fmac_f32_e32 v145, v147, v145
	v_mul_f32_e32 v147, v146, v145
	v_fma_f32 v148, -v144, v147, v146
	v_fmac_f32_e32 v147, v148, v145
	v_fma_f32 v144, -v144, v147, v146
	v_div_fmas_f32 v144, v144, v145, v147
	v_div_fixup_f32 v31, v144, v31, 1.0
	v_div_scale_f32 v144, s[20:21], v32, v32, 1.0
	v_rcp_f32_e32 v145, v144
	v_div_scale_f32 v146, vcc, 1.0, v32, 1.0
	v_fma_f32 v147, -v144, v145, 1.0
	v_fmac_f32_e32 v145, v147, v145
	v_mul_f32_e32 v147, v146, v145
	v_fma_f32 v148, -v144, v147, v146
	v_fmac_f32_e32 v147, v148, v145
	v_fma_f32 v144, -v144, v147, v146
	v_div_fmas_f32 v144, v144, v145, v147
	v_div_fixup_f32 v32, v144, v32, 1.0
	v_div_scale_f32 v144, s[20:21], v33, v33, 1.0
	v_rcp_f32_e32 v145, v144
	v_div_scale_f32 v146, vcc, 1.0, v33, 1.0
	v_fma_f32 v147, -v144, v145, 1.0
	v_fmac_f32_e32 v145, v147, v145
	v_mul_f32_e32 v147, v146, v145
	v_fma_f32 v148, -v144, v147, v146
	v_fmac_f32_e32 v147, v148, v145
	v_fma_f32 v144, -v144, v147, v146
	v_div_fmas_f32 v144, v144, v145, v147
	v_div_fixup_f32 v33, v144, v33, 1.0
	v_div_scale_f32 v144, s[20:21], v26, v26, 1.0
	v_rcp_f32_e32 v145, v144
	v_div_scale_f32 v146, vcc, 1.0, v26, 1.0
	v_fma_f32 v147, -v144, v145, 1.0
	v_fmac_f32_e32 v145, v147, v145
	v_mul_f32_e32 v147, v146, v145
	v_fma_f32 v148, -v144, v147, v146
	v_fmac_f32_e32 v147, v148, v145
	v_fma_f32 v144, -v144, v147, v146
	v_div_fmas_f32 v144, v144, v145, v147
	v_div_fixup_f32 v26, v144, v26, 1.0
	v_div_scale_f32 v144, s[20:21], v27, v27, 1.0
	v_rcp_f32_e32 v145, v144
	v_div_scale_f32 v146, vcc, 1.0, v27, 1.0
	v_fma_f32 v147, -v144, v145, 1.0
	v_fmac_f32_e32 v145, v147, v145
	v_mul_f32_e32 v147, v146, v145
	v_fma_f32 v148, -v144, v147, v146
	v_fmac_f32_e32 v147, v148, v145
	v_fma_f32 v144, -v144, v147, v146
	v_div_fmas_f32 v144, v144, v145, v147
	v_div_fixup_f32 v27, v144, v27, 1.0
	v_div_scale_f32 v144, s[20:21], v28, v28, 1.0
	v_rcp_f32_e32 v145, v144
	v_div_scale_f32 v146, vcc, 1.0, v28, 1.0
	v_fma_f32 v147, -v144, v145, 1.0
	v_fmac_f32_e32 v145, v147, v145
	v_mul_f32_e32 v147, v146, v145
	v_fma_f32 v148, -v144, v147, v146
	v_fmac_f32_e32 v147, v148, v145
	v_fma_f32 v144, -v144, v147, v146
	v_div_fmas_f32 v144, v144, v145, v147
	v_div_fixup_f32 v28, v144, v28, 1.0
	v_div_scale_f32 v144, s[20:21], v29, v29, 1.0
	v_rcp_f32_e32 v145, v144
	v_div_scale_f32 v146, vcc, 1.0, v29, 1.0
	v_fma_f32 v147, -v144, v145, 1.0
	v_fmac_f32_e32 v145, v147, v145
	v_mul_f32_e32 v147, v146, v145
	v_fma_f32 v148, -v144, v147, v146
	v_fmac_f32_e32 v147, v148, v145
	v_fma_f32 v144, -v144, v147, v146
	v_div_fmas_f32 v144, v144, v145, v147
	v_div_fixup_f32 v29, v144, v29, 1.0
	v_cvt_pk_bf16_f32 v30, v30, v31
	v_cvt_pk_bf16_f32 v31, v32, v33
	v_cvt_pk_bf16_f32 v32, v26, v27
	v_cvt_pk_bf16_f32 v33, v28, v29
	v_add_u32_e32 v157, 0xa0000, v156
	global_store_dwordx4 v157, v[30:33], s[44:45] offset:256
	v_pk_add_f32 v[22:23], v[22:23], v[10:11]
	v_pk_add_f32 v[24:25], v[24:25], v[12:13]
	v_pk_add_f32 v[18:19], v[18:19], v[14:15]
	v_pk_add_f32 v[20:21], v[20:21], v[16:17]
	v_mul_f32_e32 v22, 0xbfb8aa3b, v22
	v_mul_f32_e32 v23, 0xbfb8aa3b, v23
	v_mul_f32_e32 v24, 0xbfb8aa3b, v24
	v_mul_f32_e32 v25, 0xbfb8aa3b, v25
	v_mul_f32_e32 v18, 0xbfb8aa3b, v18
	v_mul_f32_e32 v19, 0xbfb8aa3b, v19
	v_mul_f32_e32 v20, 0xbfb8aa3b, v20
	v_mul_f32_e32 v21, 0xbfb8aa3b, v21
	v_exp_f32_e32 v22, v22
	v_exp_f32_e32 v23, v23
	v_exp_f32_e32 v24, v24
	v_exp_f32_e32 v25, v25
	v_exp_f32_e32 v18, v18
	v_exp_f32_e32 v19, v19
	v_exp_f32_e32 v20, v20
	v_exp_f32_e32 v21, v21
	v_add_f32_e32 v22, 1.0, v22
	v_add_f32_e32 v23, 1.0, v23
	v_add_f32_e32 v24, 1.0, v24
	v_add_f32_e32 v25, 1.0, v25
	v_add_f32_e32 v18, 1.0, v18
	v_add_f32_e32 v19, 1.0, v19
	v_add_f32_e32 v20, 1.0, v20
	v_add_f32_e32 v21, 1.0, v21
	v_div_scale_f32 v144, s[20:21], v22, v22, 1.0
	v_rcp_f32_e32 v145, v144
	v_div_scale_f32 v146, vcc, 1.0, v22, 1.0
	v_fma_f32 v147, -v144, v145, 1.0
	v_fmac_f32_e32 v145, v147, v145
	v_mul_f32_e32 v147, v146, v145
	v_fma_f32 v148, -v144, v147, v146
	v_fmac_f32_e32 v147, v148, v145
	v_fma_f32 v144, -v144, v147, v146
	v_div_fmas_f32 v144, v144, v145, v147
	v_div_fixup_f32 v22, v144, v22, 1.0
	v_div_scale_f32 v144, s[20:21], v23, v23, 1.0
	v_rcp_f32_e32 v145, v144
	v_div_scale_f32 v146, vcc, 1.0, v23, 1.0
	v_fma_f32 v147, -v144, v145, 1.0
	v_fmac_f32_e32 v145, v147, v145
	v_mul_f32_e32 v147, v146, v145
	v_fma_f32 v148, -v144, v147, v146
	v_fmac_f32_e32 v147, v148, v145
	v_fma_f32 v144, -v144, v147, v146
	v_div_fmas_f32 v144, v144, v145, v147
	v_div_fixup_f32 v23, v144, v23, 1.0
	v_div_scale_f32 v144, s[20:21], v24, v24, 1.0
	v_rcp_f32_e32 v145, v144
	v_div_scale_f32 v146, vcc, 1.0, v24, 1.0
	v_fma_f32 v147, -v144, v145, 1.0
	v_fmac_f32_e32 v145, v147, v145
	v_mul_f32_e32 v147, v146, v145
	v_fma_f32 v148, -v144, v147, v146
	v_fmac_f32_e32 v147, v148, v145
	v_fma_f32 v144, -v144, v147, v146
	v_div_fmas_f32 v144, v144, v145, v147
	v_div_fixup_f32 v24, v144, v24, 1.0
	v_div_scale_f32 v144, s[20:21], v25, v25, 1.0
	v_rcp_f32_e32 v145, v144
	v_div_scale_f32 v146, vcc, 1.0, v25, 1.0
	v_fma_f32 v147, -v144, v145, 1.0
	v_fmac_f32_e32 v145, v147, v145
	v_mul_f32_e32 v147, v146, v145
	v_fma_f32 v148, -v144, v147, v146
	v_fmac_f32_e32 v147, v148, v145
	v_fma_f32 v144, -v144, v147, v146
	v_div_fmas_f32 v144, v144, v145, v147
	v_div_fixup_f32 v25, v144, v25, 1.0
	v_div_scale_f32 v144, s[20:21], v18, v18, 1.0
	v_rcp_f32_e32 v145, v144
	v_div_scale_f32 v146, vcc, 1.0, v18, 1.0
	v_fma_f32 v147, -v144, v145, 1.0
	v_fmac_f32_e32 v145, v147, v145
	v_mul_f32_e32 v147, v146, v145
	v_fma_f32 v148, -v144, v147, v146
	v_fmac_f32_e32 v147, v148, v145
	v_fma_f32 v144, -v144, v147, v146
	v_div_fmas_f32 v144, v144, v145, v147
	v_div_fixup_f32 v18, v144, v18, 1.0
	v_div_scale_f32 v144, s[20:21], v19, v19, 1.0
	v_rcp_f32_e32 v145, v144
	v_div_scale_f32 v146, vcc, 1.0, v19, 1.0
	v_fma_f32 v147, -v144, v145, 1.0
	v_fmac_f32_e32 v145, v147, v145
	v_mul_f32_e32 v147, v146, v145
	v_fma_f32 v148, -v144, v147, v146
	v_fmac_f32_e32 v147, v148, v145
	v_fma_f32 v144, -v144, v147, v146
	v_div_fmas_f32 v144, v144, v145, v147
	v_div_fixup_f32 v19, v144, v19, 1.0
	v_div_scale_f32 v144, s[20:21], v20, v20, 1.0
	v_rcp_f32_e32 v145, v144
	v_div_scale_f32 v146, vcc, 1.0, v20, 1.0
	v_fma_f32 v147, -v144, v145, 1.0
	v_fmac_f32_e32 v145, v147, v145
	v_mul_f32_e32 v147, v146, v145
	v_fma_f32 v148, -v144, v147, v146
	v_fmac_f32_e32 v147, v148, v145
	v_fma_f32 v144, -v144, v147, v146
	v_div_fmas_f32 v144, v144, v145, v147
	v_div_fixup_f32 v20, v144, v20, 1.0
	v_div_scale_f32 v144, s[20:21], v21, v21, 1.0
	v_rcp_f32_e32 v145, v144
	v_div_scale_f32 v146, vcc, 1.0, v21, 1.0
	v_fma_f32 v147, -v144, v145, 1.0
	v_fmac_f32_e32 v145, v147, v145
	v_mul_f32_e32 v147, v146, v145
	v_fma_f32 v148, -v144, v147, v146
	v_fmac_f32_e32 v147, v148, v145
	v_fma_f32 v144, -v144, v147, v146
	v_div_fmas_f32 v144, v144, v145, v147
	v_div_fixup_f32 v21, v144, v21, 1.0
	v_cvt_pk_bf16_f32 v22, v22, v23
	v_cvt_pk_bf16_f32 v23, v24, v25
	v_cvt_pk_bf16_f32 v24, v18, v19
	v_cvt_pk_bf16_f32 v25, v20, v21
	v_add_u32_e32 v157, 0xb0000, v156
	s_and_b64 vcc, exec, s[4:5]
	s_mov_b64 s[4:5], -1
	global_store_dwordx4 v157, v[22:25], s[44:45] offset:256
	s_cbranch_vccnz .LBB0_566
	s_andn2_b64 vcc, exec, s[18:19]
	s_cbranch_vccnz .LBB0_565
	s_barrier
	s_branch .LBB0_565
.Llr_decay:
	s_waitcnt vmcnt(0)
	v_pk_add_f32 v[6:7], v[6:7], v[10:11]
	v_pk_add_f32 v[8:9], v[8:9], v[12:13]
	v_pk_add_f32 v[2:3], v[2:3], v[14:15]
	v_pk_add_f32 v[4:5], v[4:5], v[16:17]
	v_mul_f32_e32 v6, 0xbfb8aa3b, v6
	v_mul_f32_e32 v7, 0xbfb8aa3b, v7
	v_mul_f32_e32 v8, 0xbfb8aa3b, v8
	v_mul_f32_e32 v9, 0xbfb8aa3b, v9
	v_mul_f32_e32 v2, 0xbfb8aa3b, v2
	v_mul_f32_e32 v3, 0xbfb8aa3b, v3
	v_mul_f32_e32 v4, 0xbfb8aa3b, v4
	v_mul_f32_e32 v5, 0xbfb8aa3b, v5
	v_exp_f32_e32 v6, v6
	v_exp_f32_e32 v7, v7
	v_exp_f32_e32 v8, v8
	v_exp_f32_e32 v9, v9
	v_exp_f32_e32 v2, v2
	v_exp_f32_e32 v3, v3
	v_exp_f32_e32 v4, v4
	v_exp_f32_e32 v5, v5
	v_add_f32_e32 v6, 1.0, v6
	v_add_f32_e32 v7, 1.0, v7
	v_add_f32_e32 v8, 1.0, v8
	v_add_f32_e32 v9, 1.0, v9
	v_add_f32_e32 v2, 1.0, v2
	v_add_f32_e32 v3, 1.0, v3
	v_add_f32_e32 v4, 1.0, v4
	v_add_f32_e32 v5, 1.0, v5
	v_rcp_f32_e32 v6, v6
	v_rcp_f32_e32 v7, v7
	v_rcp_f32_e32 v8, v8
	v_rcp_f32_e32 v9, v9
	v_rcp_f32_e32 v2, v2
	v_rcp_f32_e32 v3, v3
	v_rcp_f32_e32 v4, v4
	v_rcp_f32_e32 v5, v5
	v_mul_f32_e32 v6, 0xbf60028a, v6
	v_mul_f32_e32 v7, 0xbf60028a, v7
	v_mul_f32_e32 v8, 0xbf60028a, v8
	v_mul_f32_e32 v9, 0xbf60028a, v9
	v_mul_f32_e32 v2, 0xbf60028a, v2
	v_mul_f32_e32 v3, 0xbf60028a, v3
	v_mul_f32_e32 v4, 0xbf60028a, v4
	v_mul_f32_e32 v5, 0xbf60028a, v5
	v_cvt_pk_bf16_f32 v6, v6, v7
	v_cvt_pk_bf16_f32 v7, v8, v9
	v_cvt_pk_bf16_f32 v8, v2, v3
	v_cvt_pk_bf16_f32 v9, v4, v5
	global_store_dwordx4 v156, v[6:9], s[44:45]
	v_pk_add_f32 v[134:135], v[134:135], v[10:11]
	v_pk_add_f32 v[136:137], v[136:137], v[12:13]
	v_pk_add_f32 v[130:131], v[130:131], v[14:15]
	v_pk_add_f32 v[132:133], v[132:133], v[16:17]
	v_mul_f32_e32 v134, 0xbfb8aa3b, v134
	v_mul_f32_e32 v135, 0xbfb8aa3b, v135
	v_mul_f32_e32 v136, 0xbfb8aa3b, v136
	v_mul_f32_e32 v137, 0xbfb8aa3b, v137
	v_mul_f32_e32 v130, 0xbfb8aa3b, v130
	v_mul_f32_e32 v131, 0xbfb8aa3b, v131
	v_mul_f32_e32 v132, 0xbfb8aa3b, v132
	v_mul_f32_e32 v133, 0xbfb8aa3b, v133
	v_exp_f32_e32 v134, v134
	v_exp_f32_e32 v135, v135
	v_exp_f32_e32 v136, v136
	v_exp_f32_e32 v137, v137
	v_exp_f32_e32 v130, v130
	v_exp_f32_e32 v131, v131
	v_exp_f32_e32 v132, v132
	v_exp_f32_e32 v133, v133
	v_add_f32_e32 v134, 1.0, v134
	v_add_f32_e32 v135, 1.0, v135
	v_add_f32_e32 v136, 1.0, v136
	v_add_f32_e32 v137, 1.0, v137
	v_add_f32_e32 v130, 1.0, v130
	v_add_f32_e32 v131, 1.0, v131
	v_add_f32_e32 v132, 1.0, v132
	v_add_f32_e32 v133, 1.0, v133
	v_rcp_f32_e32 v134, v134
	v_rcp_f32_e32 v135, v135
	v_rcp_f32_e32 v136, v136
	v_rcp_f32_e32 v137, v137
	v_rcp_f32_e32 v130, v130
	v_rcp_f32_e32 v131, v131
	v_rcp_f32_e32 v132, v132
	v_rcp_f32_e32 v133, v133
	v_mul_f32_e32 v134, 0xbf60028a, v134
	v_mul_f32_e32 v135, 0xbf60028a, v135
	v_mul_f32_e32 v136, 0xbf60028a, v136
	v_mul_f32_e32 v137, 0xbf60028a, v137
	v_mul_f32_e32 v130, 0xbf60028a, v130
	v_mul_f32_e32 v131, 0xbf60028a, v131
	v_mul_f32_e32 v132, 0xbf60028a, v132
	v_mul_f32_e32 v133, 0xbf60028a, v133
	v_cvt_pk_bf16_f32 v134, v134, v135
	v_cvt_pk_bf16_f32 v135, v136, v137
	v_cvt_pk_bf16_f32 v136, v130, v131
	v_cvt_pk_bf16_f32 v137, v132, v133
	v_add_u32_e32 v157, 0x10000, v156
	global_store_dwordx4 v157, v[134:137], s[44:45]
	v_pk_add_f32 v[126:127], v[126:127], v[10:11]
	v_pk_add_f32 v[128:129], v[128:129], v[12:13]
	v_pk_add_f32 v[122:123], v[122:123], v[14:15]
	v_pk_add_f32 v[124:125], v[124:125], v[16:17]
	v_mul_f32_e32 v126, 0xbfb8aa3b, v126
	v_mul_f32_e32 v127, 0xbfb8aa3b, v127
	v_mul_f32_e32 v128, 0xbfb8aa3b, v128
	v_mul_f32_e32 v129, 0xbfb8aa3b, v129
	v_mul_f32_e32 v122, 0xbfb8aa3b, v122
	v_mul_f32_e32 v123, 0xbfb8aa3b, v123
	v_mul_f32_e32 v124, 0xbfb8aa3b, v124
	v_mul_f32_e32 v125, 0xbfb8aa3b, v125
	v_exp_f32_e32 v126, v126
	v_exp_f32_e32 v127, v127
	v_exp_f32_e32 v128, v128
	v_exp_f32_e32 v129, v129
	v_exp_f32_e32 v122, v122
	v_exp_f32_e32 v123, v123
	v_exp_f32_e32 v124, v124
	v_exp_f32_e32 v125, v125
	v_add_f32_e32 v126, 1.0, v126
	v_add_f32_e32 v127, 1.0, v127
	v_add_f32_e32 v128, 1.0, v128
	v_add_f32_e32 v129, 1.0, v129
	v_add_f32_e32 v122, 1.0, v122
	v_add_f32_e32 v123, 1.0, v123
	v_add_f32_e32 v124, 1.0, v124
	v_add_f32_e32 v125, 1.0, v125
	v_rcp_f32_e32 v126, v126
	v_rcp_f32_e32 v127, v127
	v_rcp_f32_e32 v128, v128
	v_rcp_f32_e32 v129, v129
	v_rcp_f32_e32 v122, v122
	v_rcp_f32_e32 v123, v123
	v_rcp_f32_e32 v124, v124
	v_rcp_f32_e32 v125, v125
	v_mul_f32_e32 v126, 0xbf60028a, v126
	v_mul_f32_e32 v127, 0xbf60028a, v127
	v_mul_f32_e32 v128, 0xbf60028a, v128
	v_mul_f32_e32 v129, 0xbf60028a, v129
	v_mul_f32_e32 v122, 0xbf60028a, v122
	v_mul_f32_e32 v123, 0xbf60028a, v123
	v_mul_f32_e32 v124, 0xbf60028a, v124
	v_mul_f32_e32 v125, 0xbf60028a, v125
	v_cvt_pk_bf16_f32 v126, v126, v127
	v_cvt_pk_bf16_f32 v127, v128, v129
	v_cvt_pk_bf16_f32 v128, v122, v123
	v_cvt_pk_bf16_f32 v129, v124, v125
	v_add_u32_e32 v157, 0x20000, v156
	global_store_dwordx4 v157, v[126:129], s[44:45]
	v_pk_add_f32 v[118:119], v[118:119], v[10:11]
	v_pk_add_f32 v[120:121], v[120:121], v[12:13]
	v_pk_add_f32 v[114:115], v[114:115], v[14:15]
	v_pk_add_f32 v[116:117], v[116:117], v[16:17]
	v_mul_f32_e32 v118, 0xbfb8aa3b, v118
	v_mul_f32_e32 v119, 0xbfb8aa3b, v119
	v_mul_f32_e32 v120, 0xbfb8aa3b, v120
	v_mul_f32_e32 v121, 0xbfb8aa3b, v121
	v_mul_f32_e32 v114, 0xbfb8aa3b, v114
	v_mul_f32_e32 v115, 0xbfb8aa3b, v115
	v_mul_f32_e32 v116, 0xbfb8aa3b, v116
	v_mul_f32_e32 v117, 0xbfb8aa3b, v117
	v_exp_f32_e32 v118, v118
	v_exp_f32_e32 v119, v119
	v_exp_f32_e32 v120, v120
	v_exp_f32_e32 v121, v121
	v_exp_f32_e32 v114, v114
	v_exp_f32_e32 v115, v115
	v_exp_f32_e32 v116, v116
	v_exp_f32_e32 v117, v117
	v_add_f32_e32 v118, 1.0, v118
	v_add_f32_e32 v119, 1.0, v119
	v_add_f32_e32 v120, 1.0, v120
	v_add_f32_e32 v121, 1.0, v121
	v_add_f32_e32 v114, 1.0, v114
	v_add_f32_e32 v115, 1.0, v115
	v_add_f32_e32 v116, 1.0, v116
	v_add_f32_e32 v117, 1.0, v117
	v_rcp_f32_e32 v118, v118
	v_rcp_f32_e32 v119, v119
	v_rcp_f32_e32 v120, v120
	v_rcp_f32_e32 v121, v121
	v_rcp_f32_e32 v114, v114
	v_rcp_f32_e32 v115, v115
	v_rcp_f32_e32 v116, v116
	v_rcp_f32_e32 v117, v117
	v_mul_f32_e32 v118, 0xbf60028a, v118
	v_mul_f32_e32 v119, 0xbf60028a, v119
	v_mul_f32_e32 v120, 0xbf60028a, v120
	v_mul_f32_e32 v121, 0xbf60028a, v121
	v_mul_f32_e32 v114, 0xbf60028a, v114
	v_mul_f32_e32 v115, 0xbf60028a, v115
	v_mul_f32_e32 v116, 0xbf60028a, v116
	v_mul_f32_e32 v117, 0xbf60028a, v117
	v_cvt_pk_bf16_f32 v118, v118, v119
	v_cvt_pk_bf16_f32 v119, v120, v121
	v_cvt_pk_bf16_f32 v120, v114, v115
	v_cvt_pk_bf16_f32 v121, v116, v117
	v_add_u32_e32 v157, 0x30000, v156
	global_store_dwordx4 v157, v[118:121], s[44:45]
	v_pk_add_f32 v[110:111], v[110:111], v[10:11]
	v_pk_add_f32 v[112:113], v[112:113], v[12:13]
	v_pk_add_f32 v[106:107], v[106:107], v[14:15]
	v_pk_add_f32 v[108:109], v[108:109], v[16:17]
	v_mul_f32_e32 v110, 0xbfb8aa3b, v110
	v_mul_f32_e32 v111, 0xbfb8aa3b, v111
	v_mul_f32_e32 v112, 0xbfb8aa3b, v112
	v_mul_f32_e32 v113, 0xbfb8aa3b, v113
	v_mul_f32_e32 v106, 0xbfb8aa3b, v106
	v_mul_f32_e32 v107, 0xbfb8aa3b, v107
	v_mul_f32_e32 v108, 0xbfb8aa3b, v108
	v_mul_f32_e32 v109, 0xbfb8aa3b, v109
	v_exp_f32_e32 v110, v110
	v_exp_f32_e32 v111, v111
	v_exp_f32_e32 v112, v112
	v_exp_f32_e32 v113, v113
	v_exp_f32_e32 v106, v106
	v_exp_f32_e32 v107, v107
	v_exp_f32_e32 v108, v108
	v_exp_f32_e32 v109, v109
	v_add_f32_e32 v110, 1.0, v110
	v_add_f32_e32 v111, 1.0, v111
	v_add_f32_e32 v112, 1.0, v112
	v_add_f32_e32 v113, 1.0, v113
	v_add_f32_e32 v106, 1.0, v106
	v_add_f32_e32 v107, 1.0, v107
	v_add_f32_e32 v108, 1.0, v108
	v_add_f32_e32 v109, 1.0, v109
	v_rcp_f32_e32 v110, v110
	v_rcp_f32_e32 v111, v111
	v_rcp_f32_e32 v112, v112
	v_rcp_f32_e32 v113, v113
	v_rcp_f32_e32 v106, v106
	v_rcp_f32_e32 v107, v107
	v_rcp_f32_e32 v108, v108
	v_rcp_f32_e32 v109, v109
	v_mul_f32_e32 v110, 0xbf60028a, v110
	v_mul_f32_e32 v111, 0xbf60028a, v111
	v_mul_f32_e32 v112, 0xbf60028a, v112
	v_mul_f32_e32 v113, 0xbf60028a, v113
	v_mul_f32_e32 v106, 0xbf60028a, v106
	v_mul_f32_e32 v107, 0xbf60028a, v107
	v_mul_f32_e32 v108, 0xbf60028a, v108
	v_mul_f32_e32 v109, 0xbf60028a, v109
	v_cvt_pk_bf16_f32 v110, v110, v111
	v_cvt_pk_bf16_f32 v111, v112, v113
	v_cvt_pk_bf16_f32 v112, v106, v107
	v_cvt_pk_bf16_f32 v113, v108, v109
	v_add_u32_e32 v157, 0x80000, v156
	global_store_dwordx4 v157, v[110:113], s[44:45]
	v_pk_add_f32 v[102:103], v[102:103], v[10:11]
	v_pk_add_f32 v[104:105], v[104:105], v[12:13]
	v_pk_add_f32 v[98:99], v[98:99], v[14:15]
	v_pk_add_f32 v[100:101], v[100:101], v[16:17]
	v_mul_f32_e32 v102, 0xbfb8aa3b, v102
	v_mul_f32_e32 v103, 0xbfb8aa3b, v103
	v_mul_f32_e32 v104, 0xbfb8aa3b, v104
	v_mul_f32_e32 v105, 0xbfb8aa3b, v105
	v_mul_f32_e32 v98, 0xbfb8aa3b, v98
	v_mul_f32_e32 v99, 0xbfb8aa3b, v99
	v_mul_f32_e32 v100, 0xbfb8aa3b, v100
	v_mul_f32_e32 v101, 0xbfb8aa3b, v101
	v_exp_f32_e32 v102, v102
	v_exp_f32_e32 v103, v103
	v_exp_f32_e32 v104, v104
	v_exp_f32_e32 v105, v105
	v_exp_f32_e32 v98, v98
	v_exp_f32_e32 v99, v99
	v_exp_f32_e32 v100, v100
	v_exp_f32_e32 v101, v101
	v_add_f32_e32 v102, 1.0, v102
	v_add_f32_e32 v103, 1.0, v103
	v_add_f32_e32 v104, 1.0, v104
	v_add_f32_e32 v105, 1.0, v105
	v_add_f32_e32 v98, 1.0, v98
	v_add_f32_e32 v99, 1.0, v99
	v_add_f32_e32 v100, 1.0, v100
	v_add_f32_e32 v101, 1.0, v101
	v_rcp_f32_e32 v102, v102
	v_rcp_f32_e32 v103, v103
	v_rcp_f32_e32 v104, v104
	v_rcp_f32_e32 v105, v105
	v_rcp_f32_e32 v98, v98
	v_rcp_f32_e32 v99, v99
	v_rcp_f32_e32 v100, v100
	v_rcp_f32_e32 v101, v101
	v_mul_f32_e32 v102, 0xbf60028a, v102
	v_mul_f32_e32 v103, 0xbf60028a, v103
	v_mul_f32_e32 v104, 0xbf60028a, v104
	v_mul_f32_e32 v105, 0xbf60028a, v105
	v_mul_f32_e32 v98, 0xbf60028a, v98
	v_mul_f32_e32 v99, 0xbf60028a, v99
	v_mul_f32_e32 v100, 0xbf60028a, v100
	v_mul_f32_e32 v101, 0xbf60028a, v101
	v_cvt_pk_bf16_f32 v102, v102, v103
	v_cvt_pk_bf16_f32 v103, v104, v105
	v_cvt_pk_bf16_f32 v104, v98, v99
	v_cvt_pk_bf16_f32 v105, v100, v101
	v_add_u32_e32 v157, 0x90000, v156
	global_store_dwordx4 v157, v[102:105], s[44:45]
	v_pk_add_f32 v[94:95], v[94:95], v[10:11]
	v_pk_add_f32 v[96:97], v[96:97], v[12:13]
	v_pk_add_f32 v[90:91], v[90:91], v[14:15]
	v_pk_add_f32 v[92:93], v[92:93], v[16:17]
	v_mul_f32_e32 v94, 0xbfb8aa3b, v94
	v_mul_f32_e32 v95, 0xbfb8aa3b, v95
	v_mul_f32_e32 v96, 0xbfb8aa3b, v96
	v_mul_f32_e32 v97, 0xbfb8aa3b, v97
	v_mul_f32_e32 v90, 0xbfb8aa3b, v90
	v_mul_f32_e32 v91, 0xbfb8aa3b, v91
	v_mul_f32_e32 v92, 0xbfb8aa3b, v92
	v_mul_f32_e32 v93, 0xbfb8aa3b, v93
	v_exp_f32_e32 v94, v94
	v_exp_f32_e32 v95, v95
	v_exp_f32_e32 v96, v96
	v_exp_f32_e32 v97, v97
	v_exp_f32_e32 v90, v90
	v_exp_f32_e32 v91, v91
	v_exp_f32_e32 v92, v92
	v_exp_f32_e32 v93, v93
	v_add_f32_e32 v94, 1.0, v94
	v_add_f32_e32 v95, 1.0, v95
	v_add_f32_e32 v96, 1.0, v96
	v_add_f32_e32 v97, 1.0, v97
	v_add_f32_e32 v90, 1.0, v90
	v_add_f32_e32 v91, 1.0, v91
	v_add_f32_e32 v92, 1.0, v92
	v_add_f32_e32 v93, 1.0, v93
	v_rcp_f32_e32 v94, v94
	v_rcp_f32_e32 v95, v95
	v_rcp_f32_e32 v96, v96
	v_rcp_f32_e32 v97, v97
	v_rcp_f32_e32 v90, v90
	v_rcp_f32_e32 v91, v91
	v_rcp_f32_e32 v92, v92
	v_rcp_f32_e32 v93, v93
	v_mul_f32_e32 v94, 0xbf60028a, v94
	v_mul_f32_e32 v95, 0xbf60028a, v95
	v_mul_f32_e32 v96, 0xbf60028a, v96
	v_mul_f32_e32 v97, 0xbf60028a, v97
	v_mul_f32_e32 v90, 0xbf60028a, v90
	v_mul_f32_e32 v91, 0xbf60028a, v91
	v_mul_f32_e32 v92, 0xbf60028a, v92
	v_mul_f32_e32 v93, 0xbf60028a, v93
	v_cvt_pk_bf16_f32 v94, v94, v95
	v_cvt_pk_bf16_f32 v95, v96, v97
	v_cvt_pk_bf16_f32 v96, v90, v91
	v_cvt_pk_bf16_f32 v97, v92, v93
	v_add_u32_e32 v157, 0xa0000, v156
	global_store_dwordx4 v157, v[94:97], s[44:45]
	v_pk_add_f32 v[86:87], v[86:87], v[10:11]
	v_pk_add_f32 v[88:89], v[88:89], v[12:13]
	v_pk_add_f32 v[82:83], v[82:83], v[14:15]
	v_pk_add_f32 v[84:85], v[84:85], v[16:17]
	v_mul_f32_e32 v86, 0xbfb8aa3b, v86
	v_mul_f32_e32 v87, 0xbfb8aa3b, v87
	v_mul_f32_e32 v88, 0xbfb8aa3b, v88
	v_mul_f32_e32 v89, 0xbfb8aa3b, v89
	v_mul_f32_e32 v82, 0xbfb8aa3b, v82
	v_mul_f32_e32 v83, 0xbfb8aa3b, v83
	v_mul_f32_e32 v84, 0xbfb8aa3b, v84
	v_mul_f32_e32 v85, 0xbfb8aa3b, v85
	v_exp_f32_e32 v86, v86
	v_exp_f32_e32 v87, v87
	v_exp_f32_e32 v88, v88
	v_exp_f32_e32 v89, v89
	v_exp_f32_e32 v82, v82
	v_exp_f32_e32 v83, v83
	v_exp_f32_e32 v84, v84
	v_exp_f32_e32 v85, v85
	v_add_f32_e32 v86, 1.0, v86
	v_add_f32_e32 v87, 1.0, v87
	v_add_f32_e32 v88, 1.0, v88
	v_add_f32_e32 v89, 1.0, v89
	v_add_f32_e32 v82, 1.0, v82
	v_add_f32_e32 v83, 1.0, v83
	v_add_f32_e32 v84, 1.0, v84
	v_add_f32_e32 v85, 1.0, v85
	v_rcp_f32_e32 v86, v86
	v_rcp_f32_e32 v87, v87
	v_rcp_f32_e32 v88, v88
	v_rcp_f32_e32 v89, v89
	v_rcp_f32_e32 v82, v82
	v_rcp_f32_e32 v83, v83
	v_rcp_f32_e32 v84, v84
	v_rcp_f32_e32 v85, v85
	v_mul_f32_e32 v86, 0xbf60028a, v86
	v_mul_f32_e32 v87, 0xbf60028a, v87
	v_mul_f32_e32 v88, 0xbf60028a, v88
	v_mul_f32_e32 v89, 0xbf60028a, v89
	v_mul_f32_e32 v82, 0xbf60028a, v82
	v_mul_f32_e32 v83, 0xbf60028a, v83
	v_mul_f32_e32 v84, 0xbf60028a, v84
	v_mul_f32_e32 v85, 0xbf60028a, v85
	v_cvt_pk_bf16_f32 v86, v86, v87
	v_cvt_pk_bf16_f32 v87, v88, v89
	v_cvt_pk_bf16_f32 v88, v82, v83
	v_cvt_pk_bf16_f32 v89, v84, v85
	v_add_u32_e32 v157, 0xb0000, v156
	global_store_dwordx4 v157, v[86:89], s[44:45]
	global_load_dwordx4 v[10:13], v153, s[62:63] offset:512
	global_load_dwordx4 v[14:17], v153, s[62:63] offset:528
	s_waitcnt vmcnt(0)
	v_pk_add_f32 v[78:79], v[78:79], v[10:11]
	v_pk_add_f32 v[80:81], v[80:81], v[12:13]
	v_pk_add_f32 v[74:75], v[74:75], v[14:15]
	v_pk_add_f32 v[76:77], v[76:77], v[16:17]
	v_mul_f32_e32 v78, 0xbfb8aa3b, v78
	v_mul_f32_e32 v79, 0xbfb8aa3b, v79
	v_mul_f32_e32 v80, 0xbfb8aa3b, v80
	v_mul_f32_e32 v81, 0xbfb8aa3b, v81
	v_mul_f32_e32 v74, 0xbfb8aa3b, v74
	v_mul_f32_e32 v75, 0xbfb8aa3b, v75
	v_mul_f32_e32 v76, 0xbfb8aa3b, v76
	v_mul_f32_e32 v77, 0xbfb8aa3b, v77
	v_exp_f32_e32 v78, v78
	v_exp_f32_e32 v79, v79
	v_exp_f32_e32 v80, v80
	v_exp_f32_e32 v81, v81
	v_exp_f32_e32 v74, v74
	v_exp_f32_e32 v75, v75
	v_exp_f32_e32 v76, v76
	v_exp_f32_e32 v77, v77
	v_add_f32_e32 v78, 1.0, v78
	v_add_f32_e32 v79, 1.0, v79
	v_add_f32_e32 v80, 1.0, v80
	v_add_f32_e32 v81, 1.0, v81
	v_add_f32_e32 v74, 1.0, v74
	v_add_f32_e32 v75, 1.0, v75
	v_add_f32_e32 v76, 1.0, v76
	v_add_f32_e32 v77, 1.0, v77
	v_rcp_f32_e32 v78, v78
	v_rcp_f32_e32 v79, v79
	v_rcp_f32_e32 v80, v80
	v_rcp_f32_e32 v81, v81
	v_rcp_f32_e32 v74, v74
	v_rcp_f32_e32 v75, v75
	v_rcp_f32_e32 v76, v76
	v_rcp_f32_e32 v77, v77
	v_mul_f32_e32 v78, 0xbf60028a, v78
	v_mul_f32_e32 v79, 0xbf60028a, v79
	v_mul_f32_e32 v80, 0xbf60028a, v80
	v_mul_f32_e32 v81, 0xbf60028a, v81
	v_mul_f32_e32 v74, 0xbf60028a, v74
	v_mul_f32_e32 v75, 0xbf60028a, v75
	v_mul_f32_e32 v76, 0xbf60028a, v76
	v_mul_f32_e32 v77, 0xbf60028a, v77
	v_cvt_pk_bf16_f32 v78, v78, v79
	v_cvt_pk_bf16_f32 v79, v80, v81
	v_cvt_pk_bf16_f32 v80, v74, v75
	v_cvt_pk_bf16_f32 v81, v76, v77
	global_store_dwordx4 v156, v[78:81], s[44:45] offset:256
	v_pk_add_f32 v[70:71], v[70:71], v[10:11]
	v_pk_add_f32 v[72:73], v[72:73], v[12:13]
	v_pk_add_f32 v[66:67], v[66:67], v[14:15]
	v_pk_add_f32 v[68:69], v[68:69], v[16:17]
	v_mul_f32_e32 v70, 0xbfb8aa3b, v70
	v_mul_f32_e32 v71, 0xbfb8aa3b, v71
	v_mul_f32_e32 v72, 0xbfb8aa3b, v72
	v_mul_f32_e32 v73, 0xbfb8aa3b, v73
	v_mul_f32_e32 v66, 0xbfb8aa3b, v66
	v_mul_f32_e32 v67, 0xbfb8aa3b, v67
	v_mul_f32_e32 v68, 0xbfb8aa3b, v68
	v_mul_f32_e32 v69, 0xbfb8aa3b, v69
	v_exp_f32_e32 v70, v70
	v_exp_f32_e32 v71, v71
	v_exp_f32_e32 v72, v72
	v_exp_f32_e32 v73, v73
	v_exp_f32_e32 v66, v66
	v_exp_f32_e32 v67, v67
	v_exp_f32_e32 v68, v68
	v_exp_f32_e32 v69, v69
	v_add_f32_e32 v70, 1.0, v70
	v_add_f32_e32 v71, 1.0, v71
	v_add_f32_e32 v72, 1.0, v72
	v_add_f32_e32 v73, 1.0, v73
	v_add_f32_e32 v66, 1.0, v66
	v_add_f32_e32 v67, 1.0, v67
	v_add_f32_e32 v68, 1.0, v68
	v_add_f32_e32 v69, 1.0, v69
	v_rcp_f32_e32 v70, v70
	v_rcp_f32_e32 v71, v71
	v_rcp_f32_e32 v72, v72
	v_rcp_f32_e32 v73, v73
	v_rcp_f32_e32 v66, v66
	v_rcp_f32_e32 v67, v67
	v_rcp_f32_e32 v68, v68
	v_rcp_f32_e32 v69, v69
	v_mul_f32_e32 v70, 0xbf60028a, v70
	v_mul_f32_e32 v71, 0xbf60028a, v71
	v_mul_f32_e32 v72, 0xbf60028a, v72
	v_mul_f32_e32 v73, 0xbf60028a, v73
	v_mul_f32_e32 v66, 0xbf60028a, v66
	v_mul_f32_e32 v67, 0xbf60028a, v67
	v_mul_f32_e32 v68, 0xbf60028a, v68
	v_mul_f32_e32 v69, 0xbf60028a, v69
	v_cvt_pk_bf16_f32 v70, v70, v71
	v_cvt_pk_bf16_f32 v71, v72, v73
	v_cvt_pk_bf16_f32 v72, v66, v67
	v_cvt_pk_bf16_f32 v73, v68, v69
	v_add_u32_e32 v157, 0x10000, v156
	global_store_dwordx4 v157, v[70:73], s[44:45] offset:256
	v_pk_add_f32 v[62:63], v[62:63], v[10:11]
	v_pk_add_f32 v[64:65], v[64:65], v[12:13]
	v_pk_add_f32 v[58:59], v[58:59], v[14:15]
	v_pk_add_f32 v[60:61], v[60:61], v[16:17]
	v_mul_f32_e32 v62, 0xbfb8aa3b, v62
	v_mul_f32_e32 v63, 0xbfb8aa3b, v63
	v_mul_f32_e32 v64, 0xbfb8aa3b, v64
	v_mul_f32_e32 v65, 0xbfb8aa3b, v65
	v_mul_f32_e32 v58, 0xbfb8aa3b, v58
	v_mul_f32_e32 v59, 0xbfb8aa3b, v59
	v_mul_f32_e32 v60, 0xbfb8aa3b, v60
	v_mul_f32_e32 v61, 0xbfb8aa3b, v61
	v_exp_f32_e32 v62, v62
	v_exp_f32_e32 v63, v63
	v_exp_f32_e32 v64, v64
	v_exp_f32_e32 v65, v65
	v_exp_f32_e32 v58, v58
	v_exp_f32_e32 v59, v59
	v_exp_f32_e32 v60, v60
	v_exp_f32_e32 v61, v61
	v_add_f32_e32 v62, 1.0, v62
	v_add_f32_e32 v63, 1.0, v63
	v_add_f32_e32 v64, 1.0, v64
	v_add_f32_e32 v65, 1.0, v65
	v_add_f32_e32 v58, 1.0, v58
	v_add_f32_e32 v59, 1.0, v59
	v_add_f32_e32 v60, 1.0, v60
	v_add_f32_e32 v61, 1.0, v61
	v_rcp_f32_e32 v62, v62
	v_rcp_f32_e32 v63, v63
	v_rcp_f32_e32 v64, v64
	v_rcp_f32_e32 v65, v65
	v_rcp_f32_e32 v58, v58
	v_rcp_f32_e32 v59, v59
	v_rcp_f32_e32 v60, v60
	v_rcp_f32_e32 v61, v61
	v_mul_f32_e32 v62, 0xbf60028a, v62
	v_mul_f32_e32 v63, 0xbf60028a, v63
	v_mul_f32_e32 v64, 0xbf60028a, v64
	v_mul_f32_e32 v65, 0xbf60028a, v65
	v_mul_f32_e32 v58, 0xbf60028a, v58
	v_mul_f32_e32 v59, 0xbf60028a, v59
	v_mul_f32_e32 v60, 0xbf60028a, v60
	v_mul_f32_e32 v61, 0xbf60028a, v61
	v_cvt_pk_bf16_f32 v62, v62, v63
	v_cvt_pk_bf16_f32 v63, v64, v65
	v_cvt_pk_bf16_f32 v64, v58, v59
	v_cvt_pk_bf16_f32 v65, v60, v61
	v_add_u32_e32 v157, 0x20000, v156
	global_store_dwordx4 v157, v[62:65], s[44:45] offset:256
	v_pk_add_f32 v[54:55], v[54:55], v[10:11]
	v_pk_add_f32 v[56:57], v[56:57], v[12:13]
	v_pk_add_f32 v[50:51], v[50:51], v[14:15]
	v_pk_add_f32 v[52:53], v[52:53], v[16:17]
	v_mul_f32_e32 v54, 0xbfb8aa3b, v54
	v_mul_f32_e32 v55, 0xbfb8aa3b, v55
	v_mul_f32_e32 v56, 0xbfb8aa3b, v56
	v_mul_f32_e32 v57, 0xbfb8aa3b, v57
	v_mul_f32_e32 v50, 0xbfb8aa3b, v50
	v_mul_f32_e32 v51, 0xbfb8aa3b, v51
	v_mul_f32_e32 v52, 0xbfb8aa3b, v52
	v_mul_f32_e32 v53, 0xbfb8aa3b, v53
	v_exp_f32_e32 v54, v54
	v_exp_f32_e32 v55, v55
	v_exp_f32_e32 v56, v56
	v_exp_f32_e32 v57, v57
	v_exp_f32_e32 v50, v50
	v_exp_f32_e32 v51, v51
	v_exp_f32_e32 v52, v52
	v_exp_f32_e32 v53, v53
	v_add_f32_e32 v54, 1.0, v54
	v_add_f32_e32 v55, 1.0, v55
	v_add_f32_e32 v56, 1.0, v56
	v_add_f32_e32 v57, 1.0, v57
	v_add_f32_e32 v50, 1.0, v50
	v_add_f32_e32 v51, 1.0, v51
	v_add_f32_e32 v52, 1.0, v52
	v_add_f32_e32 v53, 1.0, v53
	v_rcp_f32_e32 v54, v54
	v_rcp_f32_e32 v55, v55
	v_rcp_f32_e32 v56, v56
	v_rcp_f32_e32 v57, v57
	v_rcp_f32_e32 v50, v50
	v_rcp_f32_e32 v51, v51
	v_rcp_f32_e32 v52, v52
	v_rcp_f32_e32 v53, v53
	v_mul_f32_e32 v54, 0xbf60028a, v54
	v_mul_f32_e32 v55, 0xbf60028a, v55
	v_mul_f32_e32 v56, 0xbf60028a, v56
	v_mul_f32_e32 v57, 0xbf60028a, v57
	v_mul_f32_e32 v50, 0xbf60028a, v50
	v_mul_f32_e32 v51, 0xbf60028a, v51
	v_mul_f32_e32 v52, 0xbf60028a, v52
	v_mul_f32_e32 v53, 0xbf60028a, v53
	v_cvt_pk_bf16_f32 v54, v54, v55
	v_cvt_pk_bf16_f32 v55, v56, v57
	v_cvt_pk_bf16_f32 v56, v50, v51
	v_cvt_pk_bf16_f32 v57, v52, v53
	v_add_u32_e32 v157, 0x30000, v156
	global_store_dwordx4 v157, v[54:57], s[44:45] offset:256
	v_pk_add_f32 v[46:47], v[46:47], v[10:11]
	v_pk_add_f32 v[48:49], v[48:49], v[12:13]
	v_pk_add_f32 v[42:43], v[42:43], v[14:15]
	v_pk_add_f32 v[44:45], v[44:45], v[16:17]
	v_mul_f32_e32 v46, 0xbfb8aa3b, v46
	v_mul_f32_e32 v47, 0xbfb8aa3b, v47
	v_mul_f32_e32 v48, 0xbfb8aa3b, v48
	v_mul_f32_e32 v49, 0xbfb8aa3b, v49
	v_mul_f32_e32 v42, 0xbfb8aa3b, v42
	v_mul_f32_e32 v43, 0xbfb8aa3b, v43
	v_mul_f32_e32 v44, 0xbfb8aa3b, v44
	v_mul_f32_e32 v45, 0xbfb8aa3b, v45
	v_exp_f32_e32 v46, v46
	v_exp_f32_e32 v47, v47
	v_exp_f32_e32 v48, v48
	v_exp_f32_e32 v49, v49
	v_exp_f32_e32 v42, v42
	v_exp_f32_e32 v43, v43
	v_exp_f32_e32 v44, v44
	v_exp_f32_e32 v45, v45
	v_add_f32_e32 v46, 1.0, v46
	v_add_f32_e32 v47, 1.0, v47
	v_add_f32_e32 v48, 1.0, v48
	v_add_f32_e32 v49, 1.0, v49
	v_add_f32_e32 v42, 1.0, v42
	v_add_f32_e32 v43, 1.0, v43
	v_add_f32_e32 v44, 1.0, v44
	v_add_f32_e32 v45, 1.0, v45
	v_rcp_f32_e32 v46, v46
	v_rcp_f32_e32 v47, v47
	v_rcp_f32_e32 v48, v48
	v_rcp_f32_e32 v49, v49
	v_rcp_f32_e32 v42, v42
	v_rcp_f32_e32 v43, v43
	v_rcp_f32_e32 v44, v44
	v_rcp_f32_e32 v45, v45
	v_mul_f32_e32 v46, 0xbf60028a, v46
	v_mul_f32_e32 v47, 0xbf60028a, v47
	v_mul_f32_e32 v48, 0xbf60028a, v48
	v_mul_f32_e32 v49, 0xbf60028a, v49
	v_mul_f32_e32 v42, 0xbf60028a, v42
	v_mul_f32_e32 v43, 0xbf60028a, v43
	v_mul_f32_e32 v44, 0xbf60028a, v44
	v_mul_f32_e32 v45, 0xbf60028a, v45
	v_cvt_pk_bf16_f32 v46, v46, v47
	v_cvt_pk_bf16_f32 v47, v48, v49
	v_cvt_pk_bf16_f32 v48, v42, v43
	v_cvt_pk_bf16_f32 v49, v44, v45
	v_add_u32_e32 v157, 0x80000, v156
	global_store_dwordx4 v157, v[46:49], s[44:45] offset:256
	v_pk_add_f32 v[38:39], v[38:39], v[10:11]
	v_pk_add_f32 v[40:41], v[40:41], v[12:13]
	v_pk_add_f32 v[34:35], v[34:35], v[14:15]
	v_pk_add_f32 v[36:37], v[36:37], v[16:17]
	v_mul_f32_e32 v38, 0xbfb8aa3b, v38
	v_mul_f32_e32 v39, 0xbfb8aa3b, v39
	v_mul_f32_e32 v40, 0xbfb8aa3b, v40
	v_mul_f32_e32 v41, 0xbfb8aa3b, v41
	v_mul_f32_e32 v34, 0xbfb8aa3b, v34
	v_mul_f32_e32 v35, 0xbfb8aa3b, v35
	v_mul_f32_e32 v36, 0xbfb8aa3b, v36
	v_mul_f32_e32 v37, 0xbfb8aa3b, v37
	v_exp_f32_e32 v38, v38
	v_exp_f32_e32 v39, v39
	v_exp_f32_e32 v40, v40
	v_exp_f32_e32 v41, v41
	v_exp_f32_e32 v34, v34
	v_exp_f32_e32 v35, v35
	v_exp_f32_e32 v36, v36
	v_exp_f32_e32 v37, v37
	v_add_f32_e32 v38, 1.0, v38
	v_add_f32_e32 v39, 1.0, v39
	v_add_f32_e32 v40, 1.0, v40
	v_add_f32_e32 v41, 1.0, v41
	v_add_f32_e32 v34, 1.0, v34
	v_add_f32_e32 v35, 1.0, v35
	v_add_f32_e32 v36, 1.0, v36
	v_add_f32_e32 v37, 1.0, v37
	v_rcp_f32_e32 v38, v38
	v_rcp_f32_e32 v39, v39
	v_rcp_f32_e32 v40, v40
	v_rcp_f32_e32 v41, v41
	v_rcp_f32_e32 v34, v34
	v_rcp_f32_e32 v35, v35
	v_rcp_f32_e32 v36, v36
	v_rcp_f32_e32 v37, v37
	v_mul_f32_e32 v38, 0xbf60028a, v38
	v_mul_f32_e32 v39, 0xbf60028a, v39
	v_mul_f32_e32 v40, 0xbf60028a, v40
	v_mul_f32_e32 v41, 0xbf60028a, v41
	v_mul_f32_e32 v34, 0xbf60028a, v34
	v_mul_f32_e32 v35, 0xbf60028a, v35
	v_mul_f32_e32 v36, 0xbf60028a, v36
	v_mul_f32_e32 v37, 0xbf60028a, v37
	v_cvt_pk_bf16_f32 v38, v38, v39
	v_cvt_pk_bf16_f32 v39, v40, v41
	v_cvt_pk_bf16_f32 v40, v34, v35
	v_cvt_pk_bf16_f32 v41, v36, v37
	v_add_u32_e32 v157, 0x90000, v156
	global_store_dwordx4 v157, v[38:41], s[44:45] offset:256
	v_pk_add_f32 v[30:31], v[30:31], v[10:11]
	v_pk_add_f32 v[32:33], v[32:33], v[12:13]
	v_pk_add_f32 v[26:27], v[26:27], v[14:15]
	v_pk_add_f32 v[28:29], v[28:29], v[16:17]
	v_mul_f32_e32 v30, 0xbfb8aa3b, v30
	v_mul_f32_e32 v31, 0xbfb8aa3b, v31
	v_mul_f32_e32 v32, 0xbfb8aa3b, v32
	v_mul_f32_e32 v33, 0xbfb8aa3b, v33
	v_mul_f32_e32 v26, 0xbfb8aa3b, v26
	v_mul_f32_e32 v27, 0xbfb8aa3b, v27
	v_mul_f32_e32 v28, 0xbfb8aa3b, v28
	v_mul_f32_e32 v29, 0xbfb8aa3b, v29
	v_exp_f32_e32 v30, v30
	v_exp_f32_e32 v31, v31
	v_exp_f32_e32 v32, v32
	v_exp_f32_e32 v33, v33
	v_exp_f32_e32 v26, v26
	v_exp_f32_e32 v27, v27
	v_exp_f32_e32 v28, v28
	v_exp_f32_e32 v29, v29
	v_add_f32_e32 v30, 1.0, v30
	v_add_f32_e32 v31, 1.0, v31
	v_add_f32_e32 v32, 1.0, v32
	v_add_f32_e32 v33, 1.0, v33
	v_add_f32_e32 v26, 1.0, v26
	v_add_f32_e32 v27, 1.0, v27
	v_add_f32_e32 v28, 1.0, v28
	v_add_f32_e32 v29, 1.0, v29
	v_rcp_f32_e32 v30, v30
	v_rcp_f32_e32 v31, v31
	v_rcp_f32_e32 v32, v32
	v_rcp_f32_e32 v33, v33
	v_rcp_f32_e32 v26, v26
	v_rcp_f32_e32 v27, v27
	v_rcp_f32_e32 v28, v28
	v_rcp_f32_e32 v29, v29
	v_mul_f32_e32 v30, 0xbf60028a, v30
	v_mul_f32_e32 v31, 0xbf60028a, v31
	v_mul_f32_e32 v32, 0xbf60028a, v32
	v_mul_f32_e32 v33, 0xbf60028a, v33
	v_mul_f32_e32 v26, 0xbf60028a, v26
	v_mul_f32_e32 v27, 0xbf60028a, v27
	v_mul_f32_e32 v28, 0xbf60028a, v28
	v_mul_f32_e32 v29, 0xbf60028a, v29
	v_cvt_pk_bf16_f32 v30, v30, v31
	v_cvt_pk_bf16_f32 v31, v32, v33
	v_cvt_pk_bf16_f32 v32, v26, v27
	v_cvt_pk_bf16_f32 v33, v28, v29
	v_add_u32_e32 v157, 0xa0000, v156
	global_store_dwordx4 v157, v[30:33], s[44:45] offset:256
	v_pk_add_f32 v[22:23], v[22:23], v[10:11]
	v_pk_add_f32 v[24:25], v[24:25], v[12:13]
	v_pk_add_f32 v[18:19], v[18:19], v[14:15]
	v_pk_add_f32 v[20:21], v[20:21], v[16:17]
	v_mul_f32_e32 v22, 0xbfb8aa3b, v22
	v_mul_f32_e32 v23, 0xbfb8aa3b, v23
	v_mul_f32_e32 v24, 0xbfb8aa3b, v24
	v_mul_f32_e32 v25, 0xbfb8aa3b, v25
	v_mul_f32_e32 v18, 0xbfb8aa3b, v18
	v_mul_f32_e32 v19, 0xbfb8aa3b, v19
	v_mul_f32_e32 v20, 0xbfb8aa3b, v20
	v_mul_f32_e32 v21, 0xbfb8aa3b, v21
	v_exp_f32_e32 v22, v22
	v_exp_f32_e32 v23, v23
	v_exp_f32_e32 v24, v24
	v_exp_f32_e32 v25, v25
	v_exp_f32_e32 v18, v18
	v_exp_f32_e32 v19, v19
	v_exp_f32_e32 v20, v20
	v_exp_f32_e32 v21, v21
	v_add_f32_e32 v22, 1.0, v22
	v_add_f32_e32 v23, 1.0, v23
	v_add_f32_e32 v24, 1.0, v24
	v_add_f32_e32 v25, 1.0, v25
	v_add_f32_e32 v18, 1.0, v18
	v_add_f32_e32 v19, 1.0, v19
	v_add_f32_e32 v20, 1.0, v20
	v_add_f32_e32 v21, 1.0, v21
	v_rcp_f32_e32 v22, v22
	v_rcp_f32_e32 v23, v23
	v_rcp_f32_e32 v24, v24
	v_rcp_f32_e32 v25, v25
	v_rcp_f32_e32 v18, v18
	v_rcp_f32_e32 v19, v19
	v_rcp_f32_e32 v20, v20
	v_rcp_f32_e32 v21, v21
	v_mul_f32_e32 v22, 0xbf60028a, v22
	v_mul_f32_e32 v23, 0xbf60028a, v23
	v_mul_f32_e32 v24, 0xbf60028a, v24
	v_mul_f32_e32 v25, 0xbf60028a, v25
	v_mul_f32_e32 v18, 0xbf60028a, v18
	v_mul_f32_e32 v19, 0xbf60028a, v19
	v_mul_f32_e32 v20, 0xbf60028a, v20
	v_mul_f32_e32 v21, 0xbf60028a, v21
	v_cvt_pk_bf16_f32 v22, v22, v23
	v_cvt_pk_bf16_f32 v23, v24, v25
	v_cvt_pk_bf16_f32 v24, v18, v19
	v_cvt_pk_bf16_f32 v25, v20, v21
	v_add_u32_e32 v157, 0xb0000, v156
	s_and_b64 vcc, exec, s[4:5]
	s_mov_b64 s[4:5], -1
	global_store_dwordx4 v157, v[22:25], s[44:45] offset:256
	s_cbranch_vccnz .LBB0_566
	s_andn2_b64 vcc, exec, s[18:19]
	s_cbranch_vccnz .LBB0_565
	s_barrier
	s_branch .LBB0_565
.Llr_plain:
	v_cvt_pk_bf16_f32 v6, v6, v7
	v_cvt_pk_bf16_f32 v7, v8, v9
	v_cvt_pk_bf16_f32 v8, v2, v3
	v_cvt_pk_bf16_f32 v9, v4, v5
	global_store_dwordx4 v156, v[6:9], s[44:45]
	v_cvt_pk_bf16_f32 v134, v134, v135
	v_cvt_pk_bf16_f32 v135, v136, v137
	v_cvt_pk_bf16_f32 v136, v130, v131
	v_cvt_pk_bf16_f32 v137, v132, v133
	v_add_u32_e32 v157, 0x10000, v156
	global_store_dwordx4 v157, v[134:137], s[44:45]
	v_cvt_pk_bf16_f32 v126, v126, v127
	v_cvt_pk_bf16_f32 v127, v128, v129
	v_cvt_pk_bf16_f32 v128, v122, v123
	v_cvt_pk_bf16_f32 v129, v124, v125
	v_add_u32_e32 v157, 0x20000, v156
	global_store_dwordx4 v157, v[126:129], s[44:45]
	v_cvt_pk_bf16_f32 v118, v118, v119
	v_cvt_pk_bf16_f32 v119, v120, v121
	v_cvt_pk_bf16_f32 v120, v114, v115
	v_cvt_pk_bf16_f32 v121, v116, v117
	v_add_u32_e32 v157, 0x30000, v156
	global_store_dwordx4 v157, v[118:121], s[44:45]
	v_cvt_pk_bf16_f32 v110, v110, v111
	v_cvt_pk_bf16_f32 v111, v112, v113
	v_cvt_pk_bf16_f32 v112, v106, v107
	v_cvt_pk_bf16_f32 v113, v108, v109
	v_add_u32_e32 v157, 0x80000, v156
	global_store_dwordx4 v157, v[110:113], s[44:45]
	v_cvt_pk_bf16_f32 v102, v102, v103
	v_cvt_pk_bf16_f32 v103, v104, v105
	v_cvt_pk_bf16_f32 v104, v98, v99
	v_cvt_pk_bf16_f32 v105, v100, v101
	v_add_u32_e32 v157, 0x90000, v156
	global_store_dwordx4 v157, v[102:105], s[44:45]
	v_cvt_pk_bf16_f32 v94, v94, v95
	v_cvt_pk_bf16_f32 v95, v96, v97
	v_cvt_pk_bf16_f32 v96, v90, v91
	v_cvt_pk_bf16_f32 v97, v92, v93
	v_add_u32_e32 v157, 0xa0000, v156
	global_store_dwordx4 v157, v[94:97], s[44:45]
	v_cvt_pk_bf16_f32 v86, v86, v87
	v_cvt_pk_bf16_f32 v87, v88, v89
	v_cvt_pk_bf16_f32 v88, v82, v83
	v_cvt_pk_bf16_f32 v89, v84, v85
	v_add_u32_e32 v157, 0xb0000, v156
	global_store_dwordx4 v157, v[86:89], s[44:45]
	v_cvt_pk_bf16_f32 v78, v78, v79
	v_cvt_pk_bf16_f32 v79, v80, v81
	v_cvt_pk_bf16_f32 v80, v74, v75
	v_cvt_pk_bf16_f32 v81, v76, v77
	global_store_dwordx4 v156, v[78:81], s[44:45] offset:256
	v_cvt_pk_bf16_f32 v70, v70, v71
	v_cvt_pk_bf16_f32 v71, v72, v73
	v_cvt_pk_bf16_f32 v72, v66, v67
	v_cvt_pk_bf16_f32 v73, v68, v69
	v_add_u32_e32 v157, 0x10000, v156
	global_store_dwordx4 v157, v[70:73], s[44:45] offset:256
	v_cvt_pk_bf16_f32 v62, v62, v63
	v_cvt_pk_bf16_f32 v63, v64, v65
	v_cvt_pk_bf16_f32 v64, v58, v59
	v_cvt_pk_bf16_f32 v65, v60, v61
	v_add_u32_e32 v157, 0x20000, v156
	global_store_dwordx4 v157, v[62:65], s[44:45] offset:256
	v_cvt_pk_bf16_f32 v54, v54, v55
	v_cvt_pk_bf16_f32 v55, v56, v57
	v_cvt_pk_bf16_f32 v56, v50, v51
	v_cvt_pk_bf16_f32 v57, v52, v53
	v_add_u32_e32 v157, 0x30000, v156
	global_store_dwordx4 v157, v[54:57], s[44:45] offset:256
	v_cvt_pk_bf16_f32 v46, v46, v47
	v_cvt_pk_bf16_f32 v47, v48, v49
	v_cvt_pk_bf16_f32 v48, v42, v43
	v_cvt_pk_bf16_f32 v49, v44, v45
	v_add_u32_e32 v157, 0x80000, v156
	global_store_dwordx4 v157, v[46:49], s[44:45] offset:256
	v_cvt_pk_bf16_f32 v38, v38, v39
	v_cvt_pk_bf16_f32 v39, v40, v41
	v_cvt_pk_bf16_f32 v40, v34, v35
	v_cvt_pk_bf16_f32 v41, v36, v37
	v_add_u32_e32 v157, 0x90000, v156
	global_store_dwordx4 v157, v[38:41], s[44:45] offset:256
	v_cvt_pk_bf16_f32 v30, v30, v31
	v_cvt_pk_bf16_f32 v31, v32, v33
	v_cvt_pk_bf16_f32 v32, v26, v27
	v_cvt_pk_bf16_f32 v33, v28, v29
	v_add_u32_e32 v157, 0xa0000, v156
	global_store_dwordx4 v157, v[30:33], s[44:45] offset:256
	v_cvt_pk_bf16_f32 v22, v22, v23
	v_cvt_pk_bf16_f32 v23, v24, v25
	v_cvt_pk_bf16_f32 v24, v18, v19
	v_cvt_pk_bf16_f32 v25, v20, v21
	v_add_u32_e32 v157, 0xb0000, v156
	s_and_b64 vcc, exec, s[4:5]
	s_mov_b64 s[4:5], -1
	global_store_dwordx4 v157, v[22:25], s[44:45] offset:256
	s_cbranch_vccnz .LBB0_566
	s_andn2_b64 vcc, exec, s[18:19]
	s_cbranch_vccnz .LBB0_565
	s_barrier
	s_branch .LBB0_565
